# W2 residual GEMMs (both FFNs): 256x128 block tile with register-staged A fragments, residual epilogue run per 64-row half
# speedup vs baseline: 1.4828x; 1.0199x over previous
.LBB0_153:
	s_lshr_b32 s0, s13, 6
	s_lshl_b32 s0, s0, 3
	s_and_b32 s4, s13, 7
	s_or_b32 s0, s0, s4
	s_lshl_b32 s0, s0, 8
	s_bfe_u32 s14, s13, 0x30003
	s_lshl_b32 s14, s14, 7
	v_lshrrev_b32_e32 v132, 4, v182
	v_xor_b32_e32 v132, v132, v182
	v_and_b32_e32 v132, 7, v132
	v_lshlrev_b32_e32 v132, 4, v132
	v_lshrrev_b32_e32 v133, 3, v182
	v_lshrrev_b32_e32 v134, 6, v182
	v_mul_u32_u24_e32 v180, 0x1600, v133
	v_readfirstlane_b32 s5, v134
	v_add_u32_e32 v180, v180, v132
	v_and_b32_e32 v135, 15, v182
	v_bfe_u32 v136, v182, 4, 2
	v_bfe_u32 v137, v182, 1, 3
	v_xor_b32_e32 v138, v136, v137
	v_or_b32_e32 v139, 4, v136
	v_xor_b32_e32 v139, v139, v137
	v_lshlrev_b32_e32 v138, 4, v138
	v_lshlrev_b32_e32 v139, 4, v139
	v_lshl_or_b32 v138, v135, 7, v138
	v_lshl_or_b32 v139, v135, 7, v139
	v_bfe_u32 v140, v182, 7, 1
	v_bfe_u32 v141, v182, 6, 1
	v_lshl_add_u32 v181, v140, 14, v138
	v_lshl_add_u32 v208, v140, 14, v139
	v_lshl_add_u32 v223, v141, 13, v138
	v_lshl_add_u32 v233, v141, 13, v139
	s_lshl_b32 s5, s5, 10
	s_mul_hi_u32 s15, s0, 0x1600
	s_mul_i32 s4, s0, 0x1600
	s_add_u32 s8, s30, s4
	s_addc_u32 s9, s31, s15
	s_mul_hi_u32 s15, s14, 0x1600
	s_mul_i32 s4, s14, 0x1600
	v_readlane_b32 s10, v251, 13
	v_readlane_b32 s11, v251, 14
	s_add_u32 s10, s10, s4
	s_addc_u32 s11, s11, s15
	s_mov_b32 s23, 0x8000
	s_add_u32 m0, s5, 0x0
	s_nop 0
	global_load_lds_dwordx4 v180, s[8:9]
	s_add_u32 m0, s5, 0x1000
	s_add_u32 s20, s8, 0x2c000
	s_addc_u32 s21, s9, 0
	global_load_lds_dwordx4 v180, s[20:21]
	s_add_u32 m0, s5, 0x2000
	s_add_u32 s20, s8, 0x58000
	s_addc_u32 s21, s9, 0
	global_load_lds_dwordx4 v180, s[20:21]
	s_add_u32 m0, s5, 0x3000
	s_add_u32 s20, s8, 0x84000
	s_addc_u32 s21, s9, 0
	global_load_lds_dwordx4 v180, s[20:21]
	s_add_u32 m0, s5, 0x4000
	s_add_u32 s20, s8, 0xb0000
	s_addc_u32 s21, s9, 0
	global_load_lds_dwordx4 v180, s[20:21]
	s_add_u32 m0, s5, 0x5000
	s_add_u32 s20, s8, 0xdc000
	s_addc_u32 s21, s9, 0
	global_load_lds_dwordx4 v180, s[20:21]
	s_add_u32 m0, s5, 0x6000
	s_add_u32 s20, s8, 0x108000
	s_addc_u32 s21, s9, 0
	global_load_lds_dwordx4 v180, s[20:21]
	s_add_u32 m0, s5, 0x7000
	s_add_u32 s20, s8, 0x134000
	s_addc_u32 s21, s9, 0
	global_load_lds_dwordx4 v180, s[20:21]
	s_add_u32 s8, s8, 0x80
	s_addc_u32 s9, s9, 0
	s_add_u32 m0, s5, s23
	s_nop 0
	global_load_lds_dwordx4 v180, s[10:11]
	s_add_u32 m0, m0, 0x1000
	s_add_u32 s20, s10, 0x2c000
	s_addc_u32 s21, s11, 0
	global_load_lds_dwordx4 v180, s[20:21]
	s_add_u32 m0, m0, 0x1000
	s_add_u32 s20, s10, 0x58000
	s_addc_u32 s21, s11, 0
	global_load_lds_dwordx4 v180, s[20:21]
	s_add_u32 m0, m0, 0x1000
	s_add_u32 s20, s10, 0x84000
	s_addc_u32 s21, s11, 0
	global_load_lds_dwordx4 v180, s[20:21]
	s_add_u32 s10, s10, 0x80
	s_addc_u32 s11, s11, 0
	v_mov_b32_e32 v0, 0
	v_mov_b32_e32 v1, v0
	v_mov_b32_e32 v2, v0
	v_mov_b32_e32 v3, v0
	v_mov_b32_e32 v4, v0
	v_mov_b32_e32 v5, v0
	v_mov_b32_e32 v6, v0
	v_mov_b32_e32 v7, v0
	v_mov_b32_e32 v8, v0
	v_mov_b32_e32 v9, v0
	v_mov_b32_e32 v10, v0
	v_mov_b32_e32 v11, v0
	v_mov_b32_e32 v12, v0
	v_mov_b32_e32 v13, v0
	v_mov_b32_e32 v14, v0
	v_mov_b32_e32 v15, v0
	v_mov_b32_e32 v16, v0
	v_mov_b32_e32 v17, v0
	v_mov_b32_e32 v18, v0
	v_mov_b32_e32 v19, v0
	v_mov_b32_e32 v20, v0
	v_mov_b32_e32 v21, v0
	v_mov_b32_e32 v22, v0
	v_mov_b32_e32 v23, v0
	v_mov_b32_e32 v24, v0
	v_mov_b32_e32 v25, v0
	v_mov_b32_e32 v26, v0
	v_mov_b32_e32 v27, v0
	v_mov_b32_e32 v28, v0
	v_mov_b32_e32 v29, v0
	v_mov_b32_e32 v30, v0
	v_mov_b32_e32 v31, v0
	v_mov_b32_e32 v32, v0
	v_mov_b32_e32 v33, v0
	v_mov_b32_e32 v34, v0
	v_mov_b32_e32 v35, v0
	v_mov_b32_e32 v36, v0
	v_mov_b32_e32 v37, v0
	v_mov_b32_e32 v38, v0
	v_mov_b32_e32 v39, v0
	v_mov_b32_e32 v40, v0
	v_mov_b32_e32 v41, v0
	v_mov_b32_e32 v42, v0
	v_mov_b32_e32 v43, v0
	v_mov_b32_e32 v44, v0
	v_mov_b32_e32 v45, v0
	v_mov_b32_e32 v46, v0
	v_mov_b32_e32 v47, v0
	v_mov_b32_e32 v48, v0
	v_mov_b32_e32 v49, v0
	v_mov_b32_e32 v50, v0
	v_mov_b32_e32 v51, v0
	v_mov_b32_e32 v52, v0
	v_mov_b32_e32 v53, v0
	v_mov_b32_e32 v54, v0
	v_mov_b32_e32 v55, v0
	v_mov_b32_e32 v56, v0
	v_mov_b32_e32 v57, v0
	v_mov_b32_e32 v58, v0
	v_mov_b32_e32 v59, v0
	v_mov_b32_e32 v60, v0
	v_mov_b32_e32 v61, v0
	v_mov_b32_e32 v62, v0
	v_mov_b32_e32 v63, v0
	v_mov_b32_e32 v64, v0
	v_mov_b32_e32 v65, v0
	v_mov_b32_e32 v66, v0
	v_mov_b32_e32 v67, v0
	v_mov_b32_e32 v68, v0
	v_mov_b32_e32 v69, v0
	v_mov_b32_e32 v70, v0
	v_mov_b32_e32 v71, v0
	v_mov_b32_e32 v72, v0
	v_mov_b32_e32 v73, v0
	v_mov_b32_e32 v74, v0
	v_mov_b32_e32 v75, v0
	v_mov_b32_e32 v76, v0
	v_mov_b32_e32 v77, v0
	v_mov_b32_e32 v78, v0
	v_mov_b32_e32 v79, v0
	v_mov_b32_e32 v80, v0
	v_mov_b32_e32 v81, v0
	v_mov_b32_e32 v82, v0
	v_mov_b32_e32 v83, v0
	v_mov_b32_e32 v84, v0
	v_mov_b32_e32 v85, v0
	v_mov_b32_e32 v86, v0
	v_mov_b32_e32 v87, v0
	v_mov_b32_e32 v88, v0
	v_mov_b32_e32 v89, v0
	v_mov_b32_e32 v90, v0
	v_mov_b32_e32 v91, v0
	v_mov_b32_e32 v92, v0
	v_mov_b32_e32 v93, v0
	v_mov_b32_e32 v94, v0
	v_mov_b32_e32 v95, v0
	v_mov_b32_e32 v96, v0
	v_mov_b32_e32 v97, v0
	v_mov_b32_e32 v98, v0
	v_mov_b32_e32 v99, v0
	v_mov_b32_e32 v100, v0
	v_mov_b32_e32 v101, v0
	v_mov_b32_e32 v102, v0
	v_mov_b32_e32 v103, v0
	v_mov_b32_e32 v104, v0
	v_mov_b32_e32 v105, v0
	v_mov_b32_e32 v106, v0
	v_mov_b32_e32 v107, v0
	v_mov_b32_e32 v108, v0
	v_mov_b32_e32 v109, v0
	v_mov_b32_e32 v110, v0
	v_mov_b32_e32 v111, v0
	v_mov_b32_e32 v116, v0
	v_mov_b32_e32 v117, v0
	v_mov_b32_e32 v118, v0
	v_mov_b32_e32 v119, v0
	v_mov_b32_e32 v120, v0
	v_mov_b32_e32 v121, v0
	v_mov_b32_e32 v122, v0
	v_mov_b32_e32 v123, v0
	v_mov_b32_e32 v124, v0
	v_mov_b32_e32 v125, v0
	v_mov_b32_e32 v126, v0
	v_mov_b32_e32 v127, v0
	v_mov_b32_e32 v128, v0
	v_mov_b32_e32 v129, v0
	v_mov_b32_e32 v130, v0
	v_mov_b32_e32 v131, v0
	s_movk_i32 s16, 43
.Lg4_r1:
	s_waitcnt vmcnt(0)
	s_barrier
	s_xor_b32 s23, s23, 0x4000
	s_cmp_eq_u32 s16, 0
	s_cbranch_scc1 .Lg4_r1_nb
	s_add_u32 m0, s5, s23
	s_nop 0
	global_load_lds_dwordx4 v180, s[10:11]
	s_add_u32 m0, m0, 0x1000
	s_add_u32 s20, s10, 0x2c000
	s_addc_u32 s21, s11, 0
	global_load_lds_dwordx4 v180, s[20:21]
	s_add_u32 m0, m0, 0x1000
	s_add_u32 s20, s10, 0x58000
	s_addc_u32 s21, s11, 0
	global_load_lds_dwordx4 v180, s[20:21]
	s_add_u32 m0, m0, 0x1000
	s_add_u32 s20, s10, 0x84000
	s_addc_u32 s21, s11, 0
	global_load_lds_dwordx4 v180, s[20:21]
	s_add_u32 s10, s10, 0x80
	s_addc_u32 s11, s11, 0
.Lg4_r1_nb:
	ds_read_b128 v[132:135], v181 offset:0
	ds_read_b128 v[136:139], v181 offset:2048
	ds_read_b128 v[140:143], v181 offset:4096
	ds_read_b128 v[144:147], v181 offset:6144
	ds_read_b128 v[148:151], v181 offset:8192
	ds_read_b128 v[152:155], v181 offset:10240
	ds_read_b128 v[156:159], v181 offset:12288
	ds_read_b128 v[160:163], v181 offset:14336
	ds_read_b128 v[164:167], v208 offset:0
	ds_read_b128 v[168:171], v208 offset:2048
	ds_read_b128 v[172:175], v208 offset:4096
	ds_read_b128 v[176:179], v208 offset:6144
	ds_read_b128 v[224:227], v208 offset:8192
	ds_read_b128 v[228:231], v208 offset:10240
	s_waitcnt lgkmcnt(6)
	ds_read_b128 v[234:237], v208 offset:12288
	ds_read_b128 v[238:241], v208 offset:14336
	ds_read_b128 v[242:245], v223 offset:32768
	ds_read_b128 v[112:115], v223 offset:34816
	s_waitcnt lgkmcnt(2)
	s_barrier
	s_cmp_eq_u32 s16, 0
	s_cbranch_scc1 .Lg4_r1_nl
	s_add_u32 m0, s5, 0x0
	s_nop 0
	global_load_lds_dwordx4 v180, s[8:9]
	s_add_u32 m0, s5, 0x1000
	s_add_u32 s20, s8, 0x2c000
	s_addc_u32 s21, s9, 0
	global_load_lds_dwordx4 v180, s[20:21]
	s_add_u32 m0, s5, 0x2000
	s_add_u32 s20, s8, 0x58000
	s_addc_u32 s21, s9, 0
	global_load_lds_dwordx4 v180, s[20:21]
	s_add_u32 m0, s5, 0x3000
	s_add_u32 s20, s8, 0x84000
	s_addc_u32 s21, s9, 0
	global_load_lds_dwordx4 v180, s[20:21]
	s_add_u32 m0, s5, 0x4000
	s_add_u32 s20, s8, 0xb0000
	s_addc_u32 s21, s9, 0
	global_load_lds_dwordx4 v180, s[20:21]
	s_add_u32 m0, s5, 0x5000
	s_add_u32 s20, s8, 0xdc000
	s_addc_u32 s21, s9, 0
	global_load_lds_dwordx4 v180, s[20:21]
	s_add_u32 m0, s5, 0x6000
	s_add_u32 s20, s8, 0x108000
	s_addc_u32 s21, s9, 0
	global_load_lds_dwordx4 v180, s[20:21]
	s_add_u32 m0, s5, 0x7000
	s_add_u32 s20, s8, 0x134000
	s_addc_u32 s21, s9, 0
	global_load_lds_dwordx4 v180, s[20:21]
	s_add_u32 s8, s8, 0x80
	s_addc_u32 s9, s9, 0
.Lg4_r1_nl:
	s_waitcnt lgkmcnt(1)
	v_mfma_f32_16x16x32_f16 v[0:3], v[132:135], v[242:245], v[0:3]
	v_mfma_f32_16x16x32_f16 v[16:19], v[136:139], v[242:245], v[16:19]
	v_mfma_f32_16x16x32_f16 v[32:35], v[140:143], v[242:245], v[32:35]
	v_mfma_f32_16x16x32_f16 v[48:51], v[144:147], v[242:245], v[48:51]
	v_mfma_f32_16x16x32_f16 v[64:67], v[148:151], v[242:245], v[64:67]
	v_mfma_f32_16x16x32_f16 v[80:83], v[152:155], v[242:245], v[80:83]
	v_mfma_f32_16x16x32_f16 v[96:99], v[156:159], v[242:245], v[96:99]
	v_mfma_f32_16x16x32_f16 v[116:119], v[160:163], v[242:245], v[116:119]
	ds_read_b128 v[242:245], v223 offset:36864
	s_waitcnt lgkmcnt(1)
	v_mfma_f32_16x16x32_f16 v[4:7], v[132:135], v[112:115], v[4:7]
	v_mfma_f32_16x16x32_f16 v[20:23], v[136:139], v[112:115], v[20:23]
	v_mfma_f32_16x16x32_f16 v[36:39], v[140:143], v[112:115], v[36:39]
	v_mfma_f32_16x16x32_f16 v[52:55], v[144:147], v[112:115], v[52:55]
	v_mfma_f32_16x16x32_f16 v[68:71], v[148:151], v[112:115], v[68:71]
	v_mfma_f32_16x16x32_f16 v[84:87], v[152:155], v[112:115], v[84:87]
	v_mfma_f32_16x16x32_f16 v[100:103], v[156:159], v[112:115], v[100:103]
	v_mfma_f32_16x16x32_f16 v[120:123], v[160:163], v[112:115], v[120:123]
	ds_read_b128 v[112:115], v223 offset:38912
	s_waitcnt lgkmcnt(1)
	v_mfma_f32_16x16x32_f16 v[8:11], v[132:135], v[242:245], v[8:11]
	v_mfma_f32_16x16x32_f16 v[24:27], v[136:139], v[242:245], v[24:27]
	v_mfma_f32_16x16x32_f16 v[40:43], v[140:143], v[242:245], v[40:43]
	v_mfma_f32_16x16x32_f16 v[56:59], v[144:147], v[242:245], v[56:59]
	v_mfma_f32_16x16x32_f16 v[72:75], v[148:151], v[242:245], v[72:75]
	v_mfma_f32_16x16x32_f16 v[88:91], v[152:155], v[242:245], v[88:91]
	v_mfma_f32_16x16x32_f16 v[104:107], v[156:159], v[242:245], v[104:107]
	v_mfma_f32_16x16x32_f16 v[124:127], v[160:163], v[242:245], v[124:127]
	ds_read_b128 v[242:245], v233 offset:32768
	s_waitcnt lgkmcnt(1)
	v_mfma_f32_16x16x32_f16 v[12:15], v[132:135], v[112:115], v[12:15]
	v_mfma_f32_16x16x32_f16 v[28:31], v[136:139], v[112:115], v[28:31]
	v_mfma_f32_16x16x32_f16 v[44:47], v[140:143], v[112:115], v[44:47]
	v_mfma_f32_16x16x32_f16 v[60:63], v[144:147], v[112:115], v[60:63]
	v_mfma_f32_16x16x32_f16 v[76:79], v[148:151], v[112:115], v[76:79]
	v_mfma_f32_16x16x32_f16 v[92:95], v[152:155], v[112:115], v[92:95]
	v_mfma_f32_16x16x32_f16 v[108:111], v[156:159], v[112:115], v[108:111]
	v_mfma_f32_16x16x32_f16 v[128:131], v[160:163], v[112:115], v[128:131]
	ds_read_b128 v[112:115], v233 offset:34816
	s_waitcnt lgkmcnt(1)
	v_mfma_f32_16x16x32_f16 v[0:3], v[164:167], v[242:245], v[0:3]
	v_mfma_f32_16x16x32_f16 v[16:19], v[168:171], v[242:245], v[16:19]
	v_mfma_f32_16x16x32_f16 v[32:35], v[172:175], v[242:245], v[32:35]
	v_mfma_f32_16x16x32_f16 v[48:51], v[176:179], v[242:245], v[48:51]
	v_mfma_f32_16x16x32_f16 v[64:67], v[224:227], v[242:245], v[64:67]
	v_mfma_f32_16x16x32_f16 v[80:83], v[228:231], v[242:245], v[80:83]
	v_mfma_f32_16x16x32_f16 v[96:99], v[234:237], v[242:245], v[96:99]
	v_mfma_f32_16x16x32_f16 v[116:119], v[238:241], v[242:245], v[116:119]
	ds_read_b128 v[242:245], v233 offset:36864
	s_waitcnt lgkmcnt(1)
	v_mfma_f32_16x16x32_f16 v[4:7], v[164:167], v[112:115], v[4:7]
	v_mfma_f32_16x16x32_f16 v[20:23], v[168:171], v[112:115], v[20:23]
	v_mfma_f32_16x16x32_f16 v[36:39], v[172:175], v[112:115], v[36:39]
	v_mfma_f32_16x16x32_f16 v[52:55], v[176:179], v[112:115], v[52:55]
	v_mfma_f32_16x16x32_f16 v[68:71], v[224:227], v[112:115], v[68:71]
	v_mfma_f32_16x16x32_f16 v[84:87], v[228:231], v[112:115], v[84:87]
	v_mfma_f32_16x16x32_f16 v[100:103], v[234:237], v[112:115], v[100:103]
	v_mfma_f32_16x16x32_f16 v[120:123], v[238:241], v[112:115], v[120:123]
	ds_read_b128 v[112:115], v233 offset:38912
	s_waitcnt lgkmcnt(1)
	v_mfma_f32_16x16x32_f16 v[8:11], v[164:167], v[242:245], v[8:11]
	v_mfma_f32_16x16x32_f16 v[24:27], v[168:171], v[242:245], v[24:27]
	v_mfma_f32_16x16x32_f16 v[40:43], v[172:175], v[242:245], v[40:43]
	v_mfma_f32_16x16x32_f16 v[56:59], v[176:179], v[242:245], v[56:59]
	v_mfma_f32_16x16x32_f16 v[72:75], v[224:227], v[242:245], v[72:75]
	v_mfma_f32_16x16x32_f16 v[88:91], v[228:231], v[242:245], v[88:91]
	v_mfma_f32_16x16x32_f16 v[104:107], v[234:237], v[242:245], v[104:107]
	v_mfma_f32_16x16x32_f16 v[124:127], v[238:241], v[242:245], v[124:127]
	s_waitcnt lgkmcnt(0)
	v_mfma_f32_16x16x32_f16 v[12:15], v[164:167], v[112:115], v[12:15]
	v_mfma_f32_16x16x32_f16 v[28:31], v[168:171], v[112:115], v[28:31]
	v_mfma_f32_16x16x32_f16 v[44:47], v[172:175], v[112:115], v[44:47]
	v_mfma_f32_16x16x32_f16 v[60:63], v[176:179], v[112:115], v[60:63]
	v_mfma_f32_16x16x32_f16 v[76:79], v[224:227], v[112:115], v[76:79]
	v_mfma_f32_16x16x32_f16 v[92:95], v[228:231], v[112:115], v[92:95]
	v_mfma_f32_16x16x32_f16 v[108:111], v[234:237], v[112:115], v[108:111]
	v_mfma_f32_16x16x32_f16 v[128:131], v[238:241], v[112:115], v[128:131]
	v_xor_b32_e32 v223, 0x4000, v223
	v_xor_b32_e32 v233, 0x4000, v233
	s_sub_u32 s16, s16, 1
	s_cmp_lg_u32 s16, -1
	s_cbranch_scc1 .Lg4_r1
	s_nop 7
	v_bfe_u32 v208, v182, 7, 1
	v_bfe_u32 v223, v182, 4, 2
	v_lshlrev_b32_e32 v223, 2, v223
	v_lshl_or_b32 v208, v208, 7, v223
	v_add_u32_e32 v180, s0, v208
	v_bfe_u32 v208, v182, 6, 1
	v_and_b32_e32 v223, 15, v182
	v_lshl_or_b32 v208, v208, 6, v223
	v_add_u32_e32 v208, s14, v208
	v_lshlrev_b32_e32 v181, 2, v208
	s_lshr_b32 s4, s0, 13
	s_add_i32 s4, s4, s12
	s_mul_hi_i32 s9, s4, 0x9000
	s_mul_i32 s8, s4, 0x9000
	s_add_u32 s8, s50, s8
	s_addc_u32 s9, s51, s9
	s_add_u32 s8, s8, s48
	s_addc_u32 s9, s9, 0
	v_mov_b32_e32 v247, s9
	v_add_co_u32_e32 v246, vcc, s8, v181
	v_addc_co_u32_e32 v247, vcc, 0, v247, vcc
	v_lshl_add_u32 v164, v180, 12, v181
	v_add_u32_e32 v165, 0x1000, v164
	v_add_u32_e32 v166, 0x3000, v164
	v_add_u32_e32 v167, 0x11000, v164
	v_add_u32_e32 v168, 0x13000, v164
	v_add_u32_e32 v169, 0x21000, v164
	v_add_u32_e32 v170, 0x23000, v164
	v_add_u32_e32 v171, 0x31000, v164
	v_add_u32_e32 v172, 0x33000, v164
	v_lshlrev_b32_e32 v115, 3, v180
	v_add_u32_e32 v115, 0x1e200000, v115
	v_add_u32_e32 v208, 0x2000, v181
	v_mov_b32_e32 v223, s71
	v_cmp_ne_u32_e64 s[98:99], 0, v223
	global_load_dwordx2 v[132:133], v115, s[30:31] offset:0
	global_load_dwordx2 v[134:135], v115, s[30:31] offset:8
	global_load_dwordx2 v[136:137], v115, s[30:31] offset:16
	global_load_dwordx2 v[138:139], v115, s[30:31] offset:24
	global_load_dwordx2 v[140:141], v115, s[30:31] offset:128
	global_load_dwordx2 v[142:143], v115, s[30:31] offset:136
	global_load_dwordx2 v[144:145], v115, s[30:31] offset:144
	global_load_dwordx2 v[146:147], v115, s[30:31] offset:152
	global_load_dwordx2 v[148:149], v115, s[30:31] offset:256
	global_load_dwordx2 v[150:151], v115, s[30:31] offset:264
	global_load_dwordx2 v[152:153], v115, s[30:31] offset:272
	global_load_dwordx2 v[154:155], v115, s[30:31] offset:280
	global_load_dwordx2 v[156:157], v115, s[30:31] offset:384
	global_load_dwordx2 v[158:159], v115, s[30:31] offset:392
	global_load_dwordx2 v[160:161], v115, s[30:31] offset:400
	global_load_dwordx2 v[162:163], v115, s[30:31] offset:408
	global_load_dword v239, v208, s[24:25] offset:0
	global_load_dword v243, v208, s[26:27] offset:0
	global_load_dword v240, v208, s[24:25] offset:64
	global_load_dword v244, v208, s[26:27] offset:64
	global_load_dword v241, v208, s[24:25] offset:128
	global_load_dword v245, v208, s[26:27] offset:128
	global_load_dword v242, v208, s[24:25] offset:192
	global_load_dword v112, v208, s[26:27] offset:192
	global_load_dword v173, v[246:247], off offset:0
	global_load_dword v174, v[246:247], off offset:64
	global_load_dword v175, v[246:247], off offset:128
	global_load_dword v176, v[246:247], off offset:192
	global_load_dword v177, v165, s[2:3] offset:-4096
	global_load_dword v178, v165, s[2:3] offset:0
	global_load_dword v179, v166, s[2:3] offset:-4096
	global_load_dword v224, v166, s[2:3] offset:0
	global_load_dword v225, v167, s[2:3] offset:-4096
	global_load_dword v226, v167, s[2:3] offset:0
	global_load_dword v227, v168, s[2:3] offset:-4096
	global_load_dword v228, v168, s[2:3] offset:0
	global_load_dword v229, v169, s[2:3] offset:-4096
	global_load_dword v230, v169, s[2:3] offset:0
	global_load_dword v231, v170, s[2:3] offset:-4096
	global_load_dword v234, v170, s[2:3] offset:0
	global_load_dword v235, v171, s[2:3] offset:-4096
	global_load_dword v236, v171, s[2:3] offset:0
	global_load_dword v237, v172, s[2:3] offset:-4096
	global_load_dword v238, v172, s[2:3] offset:0
	s_waitcnt vmcnt(15)
	v_add_f32_e32 v173, 1.0, v173
	v_add_f32_e32 v174, 1.0, v174
	v_add_f32_e32 v175, 1.0, v175
	v_add_f32_e32 v176, 1.0, v176
	v_mul_f32_e32 v173, 0.5, v173
	v_mul_f32_e32 v174, 0.5, v174
	v_mul_f32_e32 v175, 0.5, v175
	v_mul_f32_e32 v176, 0.5, v176
	v_sub_f32_e32 v233, v177, v132
	v_mul_f32_e32 v233, v233, v133
	v_fma_f32 v233, v239, v233, v243
	v_cndmask_b32_e64 v177, v177, v233, s[98:99]
	v_mul_f32_e32 v0, v0, v173
	v_fmac_f32_e32 v0, 0x3fb504f3, v177
	global_load_dword v177, v165, s[2:3] offset:-4032
	global_store_dword v165, v0, s[28:29] offset:-4096
	s_waitcnt vmcnt(16)
	v_sub_f32_e32 v233, v178, v134
	v_mul_f32_e32 v233, v233, v135
	v_fma_f32 v233, v239, v233, v243
	v_cndmask_b32_e64 v178, v178, v233, s[98:99]
	v_mul_f32_e32 v1, v1, v173
	v_fmac_f32_e32 v1, 0x3fb504f3, v178
	global_load_dword v178, v165, s[2:3] offset:64
	global_store_dword v165, v1, s[28:29] offset:0
	s_waitcnt vmcnt(17)
	v_sub_f32_e32 v233, v179, v136
	v_mul_f32_e32 v233, v233, v137
	v_fma_f32 v233, v239, v233, v243
	v_cndmask_b32_e64 v179, v179, v233, s[98:99]
	v_mul_f32_e32 v2, v2, v173
	v_fmac_f32_e32 v2, 0x3fb504f3, v179
	global_load_dword v179, v166, s[2:3] offset:-4032
	global_store_dword v166, v2, s[28:29] offset:-4096
	s_waitcnt vmcnt(18)
	v_sub_f32_e32 v233, v224, v138
	v_mul_f32_e32 v233, v233, v139
	v_fma_f32 v233, v239, v233, v243
	v_cndmask_b32_e64 v224, v224, v233, s[98:99]
	v_mul_f32_e32 v3, v3, v173
	v_fmac_f32_e32 v3, 0x3fb504f3, v224
	global_load_dword v224, v166, s[2:3] offset:64
	global_store_dword v166, v3, s[28:29] offset:0
	s_waitcnt vmcnt(19)
	v_sub_f32_e32 v233, v225, v140
	v_mul_f32_e32 v233, v233, v141
	v_fma_f32 v233, v239, v233, v243
	v_cndmask_b32_e64 v225, v225, v233, s[98:99]
	v_mul_f32_e32 v16, v16, v173
	v_fmac_f32_e32 v16, 0x3fb504f3, v225
	global_load_dword v225, v167, s[2:3] offset:-4032
	global_store_dword v167, v16, s[28:29] offset:-4096
	s_waitcnt vmcnt(20)
	v_sub_f32_e32 v233, v226, v142
	v_mul_f32_e32 v233, v233, v143
	v_fma_f32 v233, v239, v233, v243
	v_cndmask_b32_e64 v226, v226, v233, s[98:99]
	v_mul_f32_e32 v17, v17, v173
	v_fmac_f32_e32 v17, 0x3fb504f3, v226
	global_load_dword v226, v167, s[2:3] offset:64
	global_store_dword v167, v17, s[28:29] offset:0
	s_waitcnt vmcnt(21)
	v_sub_f32_e32 v233, v227, v144
	v_mul_f32_e32 v233, v233, v145
	v_fma_f32 v233, v239, v233, v243
	v_cndmask_b32_e64 v227, v227, v233, s[98:99]
	v_mul_f32_e32 v18, v18, v173
	v_fmac_f32_e32 v18, 0x3fb504f3, v227
	global_load_dword v227, v168, s[2:3] offset:-4032
	global_store_dword v168, v18, s[28:29] offset:-4096
	s_waitcnt vmcnt(22)
	v_sub_f32_e32 v233, v228, v146
	v_mul_f32_e32 v233, v233, v147
	v_fma_f32 v233, v239, v233, v243
	v_cndmask_b32_e64 v228, v228, v233, s[98:99]
	v_mul_f32_e32 v19, v19, v173
	v_fmac_f32_e32 v19, 0x3fb504f3, v228
	global_load_dword v228, v168, s[2:3] offset:64
	global_store_dword v168, v19, s[28:29] offset:0
	s_waitcnt vmcnt(23)
	v_sub_f32_e32 v233, v229, v148
	v_mul_f32_e32 v233, v233, v149
	v_fma_f32 v233, v239, v233, v243
	v_cndmask_b32_e64 v229, v229, v233, s[98:99]
	v_mul_f32_e32 v32, v32, v173
	v_fmac_f32_e32 v32, 0x3fb504f3, v229
	global_load_dword v229, v169, s[2:3] offset:-4032
	global_store_dword v169, v32, s[28:29] offset:-4096
	s_waitcnt vmcnt(24)
	v_sub_f32_e32 v233, v230, v150
	v_mul_f32_e32 v233, v233, v151
	v_fma_f32 v233, v239, v233, v243
	v_cndmask_b32_e64 v230, v230, v233, s[98:99]
	v_mul_f32_e32 v33, v33, v173
	v_fmac_f32_e32 v33, 0x3fb504f3, v230
	global_load_dword v230, v169, s[2:3] offset:64
	global_store_dword v169, v33, s[28:29] offset:0
	s_waitcnt vmcnt(25)
	v_sub_f32_e32 v233, v231, v152
	v_mul_f32_e32 v233, v233, v153
	v_fma_f32 v233, v239, v233, v243
	v_cndmask_b32_e64 v231, v231, v233, s[98:99]
	v_mul_f32_e32 v34, v34, v173
	v_fmac_f32_e32 v34, 0x3fb504f3, v231
	global_load_dword v231, v170, s[2:3] offset:-4032
	global_store_dword v170, v34, s[28:29] offset:-4096
	s_waitcnt vmcnt(26)
	v_sub_f32_e32 v233, v234, v154
	v_mul_f32_e32 v233, v233, v155
	v_fma_f32 v233, v239, v233, v243
	v_cndmask_b32_e64 v234, v234, v233, s[98:99]
	v_mul_f32_e32 v35, v35, v173
	v_fmac_f32_e32 v35, 0x3fb504f3, v234
	global_load_dword v234, v170, s[2:3] offset:64
	global_store_dword v170, v35, s[28:29] offset:0
	s_waitcnt vmcnt(27)
	v_sub_f32_e32 v233, v235, v156
	v_mul_f32_e32 v233, v233, v157
	v_fma_f32 v233, v239, v233, v243
	v_cndmask_b32_e64 v235, v235, v233, s[98:99]
	v_mul_f32_e32 v48, v48, v173
	v_fmac_f32_e32 v48, 0x3fb504f3, v235
	global_load_dword v235, v171, s[2:3] offset:-4032
	global_store_dword v171, v48, s[28:29] offset:-4096
	s_waitcnt vmcnt(28)
	v_sub_f32_e32 v233, v236, v158
	v_mul_f32_e32 v233, v233, v159
	v_fma_f32 v233, v239, v233, v243
	v_cndmask_b32_e64 v236, v236, v233, s[98:99]
	v_mul_f32_e32 v49, v49, v173
	v_fmac_f32_e32 v49, 0x3fb504f3, v236
	global_load_dword v236, v171, s[2:3] offset:64
	global_store_dword v171, v49, s[28:29] offset:0
	s_waitcnt vmcnt(29)
	v_sub_f32_e32 v233, v237, v160
	v_mul_f32_e32 v233, v233, v161
	v_fma_f32 v233, v239, v233, v243
	v_cndmask_b32_e64 v237, v237, v233, s[98:99]
	v_mul_f32_e32 v50, v50, v173
	v_fmac_f32_e32 v50, 0x3fb504f3, v237
	global_load_dword v237, v172, s[2:3] offset:-4032
	global_store_dword v172, v50, s[28:29] offset:-4096
	s_waitcnt vmcnt(30)
	v_sub_f32_e32 v233, v238, v162
	v_mul_f32_e32 v233, v233, v163
	v_fma_f32 v233, v239, v233, v243
	v_cndmask_b32_e64 v238, v238, v233, s[98:99]
	v_mul_f32_e32 v51, v51, v173
	v_fmac_f32_e32 v51, 0x3fb504f3, v238
	global_load_dword v238, v172, s[2:3] offset:64
	global_store_dword v172, v51, s[28:29] offset:0
	s_waitcnt vmcnt(31)
	v_sub_f32_e32 v233, v177, v132
	v_mul_f32_e32 v233, v233, v133
	v_fma_f32 v233, v240, v233, v244
	v_cndmask_b32_e64 v177, v177, v233, s[98:99]
	v_mul_f32_e32 v4, v4, v174
	v_fmac_f32_e32 v4, 0x3fb504f3, v177
	global_load_dword v177, v165, s[2:3] offset:-3968
	global_store_dword v165, v4, s[28:29] offset:-4032
	s_waitcnt vmcnt(31)
	v_sub_f32_e32 v233, v178, v134
	v_mul_f32_e32 v233, v233, v135
	v_fma_f32 v233, v240, v233, v244
	v_cndmask_b32_e64 v178, v178, v233, s[98:99]
	v_mul_f32_e32 v5, v5, v174
	v_fmac_f32_e32 v5, 0x3fb504f3, v178
	global_load_dword v178, v165, s[2:3] offset:128
	global_store_dword v165, v5, s[28:29] offset:64
	s_waitcnt vmcnt(31)
	v_sub_f32_e32 v233, v179, v136
	v_mul_f32_e32 v233, v233, v137
	v_fma_f32 v233, v240, v233, v244
	v_cndmask_b32_e64 v179, v179, v233, s[98:99]
	v_mul_f32_e32 v6, v6, v174
	v_fmac_f32_e32 v6, 0x3fb504f3, v179
	global_load_dword v179, v166, s[2:3] offset:-3968
	global_store_dword v166, v6, s[28:29] offset:-4032
	s_waitcnt vmcnt(31)
	v_sub_f32_e32 v233, v224, v138
	v_mul_f32_e32 v233, v233, v139
	v_fma_f32 v233, v240, v233, v244
	v_cndmask_b32_e64 v224, v224, v233, s[98:99]
	v_mul_f32_e32 v7, v7, v174
	v_fmac_f32_e32 v7, 0x3fb504f3, v224
	global_load_dword v224, v166, s[2:3] offset:128
	global_store_dword v166, v7, s[28:29] offset:64
	s_waitcnt vmcnt(31)
	v_sub_f32_e32 v233, v225, v140
	v_mul_f32_e32 v233, v233, v141
	v_fma_f32 v233, v240, v233, v244
	v_cndmask_b32_e64 v225, v225, v233, s[98:99]
	v_mul_f32_e32 v20, v20, v174
	v_fmac_f32_e32 v20, 0x3fb504f3, v225
	global_load_dword v225, v167, s[2:3] offset:-3968
	global_store_dword v167, v20, s[28:29] offset:-4032
	s_waitcnt vmcnt(31)
	v_sub_f32_e32 v233, v226, v142
	v_mul_f32_e32 v233, v233, v143
	v_fma_f32 v233, v240, v233, v244
	v_cndmask_b32_e64 v226, v226, v233, s[98:99]
	v_mul_f32_e32 v21, v21, v174
	v_fmac_f32_e32 v21, 0x3fb504f3, v226
	global_load_dword v226, v167, s[2:3] offset:128
	global_store_dword v167, v21, s[28:29] offset:64
	s_waitcnt vmcnt(31)
	v_sub_f32_e32 v233, v227, v144
	v_mul_f32_e32 v233, v233, v145
	v_fma_f32 v233, v240, v233, v244
	v_cndmask_b32_e64 v227, v227, v233, s[98:99]
	v_mul_f32_e32 v22, v22, v174
	v_fmac_f32_e32 v22, 0x3fb504f3, v227
	global_load_dword v227, v168, s[2:3] offset:-3968
	global_store_dword v168, v22, s[28:29] offset:-4032
	s_waitcnt vmcnt(31)
	v_sub_f32_e32 v233, v228, v146
	v_mul_f32_e32 v233, v233, v147
	v_fma_f32 v233, v240, v233, v244
	v_cndmask_b32_e64 v228, v228, v233, s[98:99]
	v_mul_f32_e32 v23, v23, v174
	v_fmac_f32_e32 v23, 0x3fb504f3, v228
	global_load_dword v228, v168, s[2:3] offset:128
	global_store_dword v168, v23, s[28:29] offset:64
	s_waitcnt vmcnt(31)
	v_sub_f32_e32 v233, v229, v148
	v_mul_f32_e32 v233, v233, v149
	v_fma_f32 v233, v240, v233, v244
	v_cndmask_b32_e64 v229, v229, v233, s[98:99]
	v_mul_f32_e32 v36, v36, v174
	v_fmac_f32_e32 v36, 0x3fb504f3, v229
	global_load_dword v229, v169, s[2:3] offset:-3968
	global_store_dword v169, v36, s[28:29] offset:-4032
	s_waitcnt vmcnt(31)
	v_sub_f32_e32 v233, v230, v150
	v_mul_f32_e32 v233, v233, v151
	v_fma_f32 v233, v240, v233, v244
	v_cndmask_b32_e64 v230, v230, v233, s[98:99]
	v_mul_f32_e32 v37, v37, v174
	v_fmac_f32_e32 v37, 0x3fb504f3, v230
	global_load_dword v230, v169, s[2:3] offset:128
	global_store_dword v169, v37, s[28:29] offset:64
	s_waitcnt vmcnt(31)
	v_sub_f32_e32 v233, v231, v152
	v_mul_f32_e32 v233, v233, v153
	v_fma_f32 v233, v240, v233, v244
	v_cndmask_b32_e64 v231, v231, v233, s[98:99]
	v_mul_f32_e32 v38, v38, v174
	v_fmac_f32_e32 v38, 0x3fb504f3, v231
	global_load_dword v231, v170, s[2:3] offset:-3968
	global_store_dword v170, v38, s[28:29] offset:-4032
	s_waitcnt vmcnt(31)
	v_sub_f32_e32 v233, v234, v154
	v_mul_f32_e32 v233, v233, v155
	v_fma_f32 v233, v240, v233, v244
	v_cndmask_b32_e64 v234, v234, v233, s[98:99]
	v_mul_f32_e32 v39, v39, v174
	v_fmac_f32_e32 v39, 0x3fb504f3, v234
	global_load_dword v234, v170, s[2:3] offset:128
	global_store_dword v170, v39, s[28:29] offset:64
	s_waitcnt vmcnt(31)
	v_sub_f32_e32 v233, v235, v156
	v_mul_f32_e32 v233, v233, v157
	v_fma_f32 v233, v240, v233, v244
	v_cndmask_b32_e64 v235, v235, v233, s[98:99]
	v_mul_f32_e32 v52, v52, v174
	v_fmac_f32_e32 v52, 0x3fb504f3, v235
	global_load_dword v235, v171, s[2:3] offset:-3968
	global_store_dword v171, v52, s[28:29] offset:-4032
	s_waitcnt vmcnt(31)
	v_sub_f32_e32 v233, v236, v158
	v_mul_f32_e32 v233, v233, v159
	v_fma_f32 v233, v240, v233, v244
	v_cndmask_b32_e64 v236, v236, v233, s[98:99]
	v_mul_f32_e32 v53, v53, v174
	v_fmac_f32_e32 v53, 0x3fb504f3, v236
	global_load_dword v236, v171, s[2:3] offset:128
	global_store_dword v171, v53, s[28:29] offset:64
	s_waitcnt vmcnt(31)
	v_sub_f32_e32 v233, v237, v160
	v_mul_f32_e32 v233, v233, v161
	v_fma_f32 v233, v240, v233, v244
	v_cndmask_b32_e64 v237, v237, v233, s[98:99]
	v_mul_f32_e32 v54, v54, v174
	v_fmac_f32_e32 v54, 0x3fb504f3, v237
	global_load_dword v237, v172, s[2:3] offset:-3968
	global_store_dword v172, v54, s[28:29] offset:-4032
	s_waitcnt vmcnt(31)
	v_sub_f32_e32 v233, v238, v162
	v_mul_f32_e32 v233, v233, v163
	v_fma_f32 v233, v240, v233, v244
	v_cndmask_b32_e64 v238, v238, v233, s[98:99]
	v_mul_f32_e32 v55, v55, v174
	v_fmac_f32_e32 v55, 0x3fb504f3, v238
	global_load_dword v238, v172, s[2:3] offset:128
	global_store_dword v172, v55, s[28:29] offset:64
	s_waitcnt vmcnt(31)
	v_sub_f32_e32 v233, v177, v132
	v_mul_f32_e32 v233, v233, v133
	v_fma_f32 v233, v241, v233, v245
	v_cndmask_b32_e64 v177, v177, v233, s[98:99]
	v_mul_f32_e32 v8, v8, v175
	v_fmac_f32_e32 v8, 0x3fb504f3, v177
	global_load_dword v177, v165, s[2:3] offset:-3904
	global_store_dword v165, v8, s[28:29] offset:-3968
	s_waitcnt vmcnt(31)
	v_sub_f32_e32 v233, v178, v134
	v_mul_f32_e32 v233, v233, v135
	v_fma_f32 v233, v241, v233, v245
	v_cndmask_b32_e64 v178, v178, v233, s[98:99]
	v_mul_f32_e32 v9, v9, v175
	v_fmac_f32_e32 v9, 0x3fb504f3, v178
	global_load_dword v178, v165, s[2:3] offset:192
	global_store_dword v165, v9, s[28:29] offset:128
	s_waitcnt vmcnt(31)
	v_sub_f32_e32 v233, v179, v136
	v_mul_f32_e32 v233, v233, v137
	v_fma_f32 v233, v241, v233, v245
	v_cndmask_b32_e64 v179, v179, v233, s[98:99]
	v_mul_f32_e32 v10, v10, v175
	v_fmac_f32_e32 v10, 0x3fb504f3, v179
	global_load_dword v179, v166, s[2:3] offset:-3904
	global_store_dword v166, v10, s[28:29] offset:-3968
	s_waitcnt vmcnt(31)
	v_sub_f32_e32 v233, v224, v138
	v_mul_f32_e32 v233, v233, v139
	v_fma_f32 v233, v241, v233, v245
	v_cndmask_b32_e64 v224, v224, v233, s[98:99]
	v_mul_f32_e32 v11, v11, v175
	v_fmac_f32_e32 v11, 0x3fb504f3, v224
	global_load_dword v224, v166, s[2:3] offset:192
	global_store_dword v166, v11, s[28:29] offset:128
	s_waitcnt vmcnt(31)
	v_sub_f32_e32 v233, v225, v140
	v_mul_f32_e32 v233, v233, v141
	v_fma_f32 v233, v241, v233, v245
	v_cndmask_b32_e64 v225, v225, v233, s[98:99]
	v_mul_f32_e32 v24, v24, v175
	v_fmac_f32_e32 v24, 0x3fb504f3, v225
	global_load_dword v225, v167, s[2:3] offset:-3904
	global_store_dword v167, v24, s[28:29] offset:-3968
	s_waitcnt vmcnt(31)
	v_sub_f32_e32 v233, v226, v142
	v_mul_f32_e32 v233, v233, v143
	v_fma_f32 v233, v241, v233, v245
	v_cndmask_b32_e64 v226, v226, v233, s[98:99]
	v_mul_f32_e32 v25, v25, v175
	v_fmac_f32_e32 v25, 0x3fb504f3, v226
	global_load_dword v226, v167, s[2:3] offset:192
	global_store_dword v167, v25, s[28:29] offset:128
	s_waitcnt vmcnt(31)
	v_sub_f32_e32 v233, v227, v144
	v_mul_f32_e32 v233, v233, v145
	v_fma_f32 v233, v241, v233, v245
	v_cndmask_b32_e64 v227, v227, v233, s[98:99]
	v_mul_f32_e32 v26, v26, v175
	v_fmac_f32_e32 v26, 0x3fb504f3, v227
	global_load_dword v227, v168, s[2:3] offset:-3904
	global_store_dword v168, v26, s[28:29] offset:-3968
	s_waitcnt vmcnt(31)
	v_sub_f32_e32 v233, v228, v146
	v_mul_f32_e32 v233, v233, v147
	v_fma_f32 v233, v241, v233, v245
	v_cndmask_b32_e64 v228, v228, v233, s[98:99]
	v_mul_f32_e32 v27, v27, v175
	v_fmac_f32_e32 v27, 0x3fb504f3, v228
	global_load_dword v228, v168, s[2:3] offset:192
	global_store_dword v168, v27, s[28:29] offset:128
	s_waitcnt vmcnt(31)
	v_sub_f32_e32 v233, v229, v148
	v_mul_f32_e32 v233, v233, v149
	v_fma_f32 v233, v241, v233, v245
	v_cndmask_b32_e64 v229, v229, v233, s[98:99]
	v_mul_f32_e32 v40, v40, v175
	v_fmac_f32_e32 v40, 0x3fb504f3, v229
	global_load_dword v229, v169, s[2:3] offset:-3904
	global_store_dword v169, v40, s[28:29] offset:-3968
	s_waitcnt vmcnt(31)
	v_sub_f32_e32 v233, v230, v150
	v_mul_f32_e32 v233, v233, v151
	v_fma_f32 v233, v241, v233, v245
	v_cndmask_b32_e64 v230, v230, v233, s[98:99]
	v_mul_f32_e32 v41, v41, v175
	v_fmac_f32_e32 v41, 0x3fb504f3, v230
	global_load_dword v230, v169, s[2:3] offset:192
	global_store_dword v169, v41, s[28:29] offset:128
	s_waitcnt vmcnt(31)
	v_sub_f32_e32 v233, v231, v152
	v_mul_f32_e32 v233, v233, v153
	v_fma_f32 v233, v241, v233, v245
	v_cndmask_b32_e64 v231, v231, v233, s[98:99]
	v_mul_f32_e32 v42, v42, v175
	v_fmac_f32_e32 v42, 0x3fb504f3, v231
	global_load_dword v231, v170, s[2:3] offset:-3904
	global_store_dword v170, v42, s[28:29] offset:-3968
	s_waitcnt vmcnt(31)
	v_sub_f32_e32 v233, v234, v154
	v_mul_f32_e32 v233, v233, v155
	v_fma_f32 v233, v241, v233, v245
	v_cndmask_b32_e64 v234, v234, v233, s[98:99]
	v_mul_f32_e32 v43, v43, v175
	v_fmac_f32_e32 v43, 0x3fb504f3, v234
	global_load_dword v234, v170, s[2:3] offset:192
	global_store_dword v170, v43, s[28:29] offset:128
	s_waitcnt vmcnt(31)
	v_sub_f32_e32 v233, v235, v156
	v_mul_f32_e32 v233, v233, v157
	v_fma_f32 v233, v241, v233, v245
	v_cndmask_b32_e64 v235, v235, v233, s[98:99]
	v_mul_f32_e32 v56, v56, v175
	v_fmac_f32_e32 v56, 0x3fb504f3, v235
	global_load_dword v235, v171, s[2:3] offset:-3904
	global_store_dword v171, v56, s[28:29] offset:-3968
	s_waitcnt vmcnt(31)
	v_sub_f32_e32 v233, v236, v158
	v_mul_f32_e32 v233, v233, v159
	v_fma_f32 v233, v241, v233, v245
	v_cndmask_b32_e64 v236, v236, v233, s[98:99]
	v_mul_f32_e32 v57, v57, v175
	v_fmac_f32_e32 v57, 0x3fb504f3, v236
	global_load_dword v236, v171, s[2:3] offset:192
	global_store_dword v171, v57, s[28:29] offset:128
	s_waitcnt vmcnt(31)
	v_sub_f32_e32 v233, v237, v160
	v_mul_f32_e32 v233, v233, v161
	v_fma_f32 v233, v241, v233, v245
	v_cndmask_b32_e64 v237, v237, v233, s[98:99]
	v_mul_f32_e32 v58, v58, v175
	v_fmac_f32_e32 v58, 0x3fb504f3, v237
	global_load_dword v237, v172, s[2:3] offset:-3904
	global_store_dword v172, v58, s[28:29] offset:-3968
	s_waitcnt vmcnt(31)
	v_sub_f32_e32 v233, v238, v162
	v_mul_f32_e32 v233, v233, v163
	v_fma_f32 v233, v241, v233, v245
	v_cndmask_b32_e64 v238, v238, v233, s[98:99]
	v_mul_f32_e32 v59, v59, v175
	v_fmac_f32_e32 v59, 0x3fb504f3, v238
	global_load_dword v238, v172, s[2:3] offset:192
	global_store_dword v172, v59, s[28:29] offset:128
	s_waitcnt vmcnt(31)
	v_sub_f32_e32 v233, v177, v132
	v_mul_f32_e32 v233, v233, v133
	v_fma_f32 v233, v242, v233, v112
	v_cndmask_b32_e64 v177, v177, v233, s[98:99]
	v_mul_f32_e32 v12, v12, v176
	v_fmac_f32_e32 v12, 0x3fb504f3, v177
	global_store_dword v165, v12, s[28:29] offset:-3904
	s_waitcnt vmcnt(30)
	v_sub_f32_e32 v233, v178, v134
	v_mul_f32_e32 v233, v233, v135
	v_fma_f32 v233, v242, v233, v112
	v_cndmask_b32_e64 v178, v178, v233, s[98:99]
	v_mul_f32_e32 v13, v13, v176
	v_fmac_f32_e32 v13, 0x3fb504f3, v178
	global_store_dword v165, v13, s[28:29] offset:192
	s_waitcnt vmcnt(29)
	v_sub_f32_e32 v233, v179, v136
	v_mul_f32_e32 v233, v233, v137
	v_fma_f32 v233, v242, v233, v112
	v_cndmask_b32_e64 v179, v179, v233, s[98:99]
	v_mul_f32_e32 v14, v14, v176
	v_fmac_f32_e32 v14, 0x3fb504f3, v179
	global_store_dword v166, v14, s[28:29] offset:-3904
	s_waitcnt vmcnt(28)
	v_sub_f32_e32 v233, v224, v138
	v_mul_f32_e32 v233, v233, v139
	v_fma_f32 v233, v242, v233, v112
	v_cndmask_b32_e64 v224, v224, v233, s[98:99]
	v_mul_f32_e32 v15, v15, v176
	v_fmac_f32_e32 v15, 0x3fb504f3, v224
	global_store_dword v166, v15, s[28:29] offset:192
	s_waitcnt vmcnt(27)
	v_sub_f32_e32 v233, v225, v140
	v_mul_f32_e32 v233, v233, v141
	v_fma_f32 v233, v242, v233, v112
	v_cndmask_b32_e64 v225, v225, v233, s[98:99]
	v_mul_f32_e32 v28, v28, v176
	v_fmac_f32_e32 v28, 0x3fb504f3, v225
	global_store_dword v167, v28, s[28:29] offset:-3904
	s_waitcnt vmcnt(26)
	v_sub_f32_e32 v233, v226, v142
	v_mul_f32_e32 v233, v233, v143
	v_fma_f32 v233, v242, v233, v112
	v_cndmask_b32_e64 v226, v226, v233, s[98:99]
	v_mul_f32_e32 v29, v29, v176
	v_fmac_f32_e32 v29, 0x3fb504f3, v226
	global_store_dword v167, v29, s[28:29] offset:192
	s_waitcnt vmcnt(25)
	v_sub_f32_e32 v233, v227, v144
	v_mul_f32_e32 v233, v233, v145
	v_fma_f32 v233, v242, v233, v112
	v_cndmask_b32_e64 v227, v227, v233, s[98:99]
	v_mul_f32_e32 v30, v30, v176
	v_fmac_f32_e32 v30, 0x3fb504f3, v227
	global_store_dword v168, v30, s[28:29] offset:-3904
	s_waitcnt vmcnt(24)
	v_sub_f32_e32 v233, v228, v146
	v_mul_f32_e32 v233, v233, v147
	v_fma_f32 v233, v242, v233, v112
	v_cndmask_b32_e64 v228, v228, v233, s[98:99]
	v_mul_f32_e32 v31, v31, v176
	v_fmac_f32_e32 v31, 0x3fb504f3, v228
	global_store_dword v168, v31, s[28:29] offset:192
	s_waitcnt vmcnt(23)
	v_sub_f32_e32 v233, v229, v148
	v_mul_f32_e32 v233, v233, v149
	v_fma_f32 v233, v242, v233, v112
	v_cndmask_b32_e64 v229, v229, v233, s[98:99]
	v_mul_f32_e32 v44, v44, v176
	v_fmac_f32_e32 v44, 0x3fb504f3, v229
	global_store_dword v169, v44, s[28:29] offset:-3904
	s_waitcnt vmcnt(22)
	v_sub_f32_e32 v233, v230, v150
	v_mul_f32_e32 v233, v233, v151
	v_fma_f32 v233, v242, v233, v112
	v_cndmask_b32_e64 v230, v230, v233, s[98:99]
	v_mul_f32_e32 v45, v45, v176
	v_fmac_f32_e32 v45, 0x3fb504f3, v230
	global_store_dword v169, v45, s[28:29] offset:192
	s_waitcnt vmcnt(21)
	v_sub_f32_e32 v233, v231, v152
	v_mul_f32_e32 v233, v233, v153
	v_fma_f32 v233, v242, v233, v112
	v_cndmask_b32_e64 v231, v231, v233, s[98:99]
	v_mul_f32_e32 v46, v46, v176
	v_fmac_f32_e32 v46, 0x3fb504f3, v231
	global_store_dword v170, v46, s[28:29] offset:-3904
	s_waitcnt vmcnt(20)
	v_sub_f32_e32 v233, v234, v154
	v_mul_f32_e32 v233, v233, v155
	v_fma_f32 v233, v242, v233, v112
	v_cndmask_b32_e64 v234, v234, v233, s[98:99]
	v_mul_f32_e32 v47, v47, v176
	v_fmac_f32_e32 v47, 0x3fb504f3, v234
	global_store_dword v170, v47, s[28:29] offset:192
	s_waitcnt vmcnt(19)
	v_sub_f32_e32 v233, v235, v156
	v_mul_f32_e32 v233, v233, v157
	v_fma_f32 v233, v242, v233, v112
	v_cndmask_b32_e64 v235, v235, v233, s[98:99]
	v_mul_f32_e32 v60, v60, v176
	v_fmac_f32_e32 v60, 0x3fb504f3, v235
	global_store_dword v171, v60, s[28:29] offset:-3904
	s_waitcnt vmcnt(18)
	v_sub_f32_e32 v233, v236, v158
	v_mul_f32_e32 v233, v233, v159
	v_fma_f32 v233, v242, v233, v112
	v_cndmask_b32_e64 v236, v236, v233, s[98:99]
	v_mul_f32_e32 v61, v61, v176
	v_fmac_f32_e32 v61, 0x3fb504f3, v236
	global_store_dword v171, v61, s[28:29] offset:192
	s_waitcnt vmcnt(17)
	v_sub_f32_e32 v233, v237, v160
	v_mul_f32_e32 v233, v233, v161
	v_fma_f32 v233, v242, v233, v112
	v_cndmask_b32_e64 v237, v237, v233, s[98:99]
	v_mul_f32_e32 v62, v62, v176
	v_fmac_f32_e32 v62, 0x3fb504f3, v237
	global_store_dword v172, v62, s[28:29] offset:-3904
	s_waitcnt vmcnt(16)
	v_sub_f32_e32 v233, v238, v162
	v_mul_f32_e32 v233, v233, v163
	v_fma_f32 v233, v242, v233, v112
	v_cndmask_b32_e64 v238, v238, v233, s[98:99]
	v_mul_f32_e32 v63, v63, v176
	v_fmac_f32_e32 v63, 0x3fb504f3, v238
	global_store_dword v172, v63, s[28:29] offset:192
	v_add_u32_e32 v180, 64, v180
	v_lshl_add_u32 v164, v180, 12, v181
	v_add_u32_e32 v165, 0x1000, v164
	v_add_u32_e32 v166, 0x3000, v164
	v_add_u32_e32 v167, 0x11000, v164
	v_add_u32_e32 v168, 0x13000, v164
	v_add_u32_e32 v169, 0x21000, v164
	v_add_u32_e32 v170, 0x23000, v164
	v_add_u32_e32 v171, 0x31000, v164
	v_add_u32_e32 v172, 0x33000, v164
	v_lshlrev_b32_e32 v35, 3, v180
	v_add_u32_e32 v35, 0x1e200000, v35
	v_add_u32_e32 v48, 0x2000, v181
	v_mov_b32_e32 v49, s71
	v_cmp_ne_u32_e64 s[98:99], 0, v49
	global_load_dwordx2 v[132:133], v35, s[30:31] offset:0
	global_load_dwordx2 v[134:135], v35, s[30:31] offset:8
	global_load_dwordx2 v[136:137], v35, s[30:31] offset:16
	global_load_dwordx2 v[138:139], v35, s[30:31] offset:24
	global_load_dwordx2 v[140:141], v35, s[30:31] offset:128
	global_load_dwordx2 v[142:143], v35, s[30:31] offset:136
	global_load_dwordx2 v[144:145], v35, s[30:31] offset:144
	global_load_dwordx2 v[146:147], v35, s[30:31] offset:152
	global_load_dwordx2 v[148:149], v35, s[30:31] offset:256
	global_load_dwordx2 v[150:151], v35, s[30:31] offset:264
	global_load_dwordx2 v[152:153], v35, s[30:31] offset:272
	global_load_dwordx2 v[154:155], v35, s[30:31] offset:280
	global_load_dwordx2 v[156:157], v35, s[30:31] offset:384
	global_load_dwordx2 v[158:159], v35, s[30:31] offset:392
	global_load_dwordx2 v[160:161], v35, s[30:31] offset:400
	global_load_dwordx2 v[162:163], v35, s[30:31] offset:408
	global_load_dword v3, v48, s[24:25] offset:0
	global_load_dword v19, v48, s[26:27] offset:0
	global_load_dword v16, v48, s[24:25] offset:64
	global_load_dword v32, v48, s[26:27] offset:64
	global_load_dword v17, v48, s[24:25] offset:128
	global_load_dword v33, v48, s[26:27] offset:128
	global_load_dword v18, v48, s[24:25] offset:192
	global_load_dword v34, v48, s[26:27] offset:192
	global_load_dword v173, v[246:247], off offset:0
	global_load_dword v174, v[246:247], off offset:64
	global_load_dword v175, v[246:247], off offset:128
	global_load_dword v176, v[246:247], off offset:192
	global_load_dword v177, v165, s[2:3] offset:-4096
	global_load_dword v178, v165, s[2:3] offset:0
	global_load_dword v179, v166, s[2:3] offset:-4096
	global_load_dword v224, v166, s[2:3] offset:0
	global_load_dword v225, v167, s[2:3] offset:-4096
	global_load_dword v226, v167, s[2:3] offset:0
	global_load_dword v227, v168, s[2:3] offset:-4096
	global_load_dword v228, v168, s[2:3] offset:0
	global_load_dword v229, v169, s[2:3] offset:-4096
	global_load_dword v230, v169, s[2:3] offset:0
	global_load_dword v231, v170, s[2:3] offset:-4096
	global_load_dword v234, v170, s[2:3] offset:0
	global_load_dword v235, v171, s[2:3] offset:-4096
	global_load_dword v236, v171, s[2:3] offset:0
	global_load_dword v237, v172, s[2:3] offset:-4096
	global_load_dword v238, v172, s[2:3] offset:0
	global_load_dword v239, v165, s[2:3] offset:-4032
	global_load_dword v240, v165, s[2:3] offset:64
	global_load_dword v241, v166, s[2:3] offset:-4032
	global_load_dword v242, v166, s[2:3] offset:64
	global_load_dword v243, v167, s[2:3] offset:-4032
	global_load_dword v244, v167, s[2:3] offset:64
	global_load_dword v245, v168, s[2:3] offset:-4032
	global_load_dword v112, v168, s[2:3] offset:64
	global_load_dword v115, v169, s[2:3] offset:-4032
	global_load_dword v208, v169, s[2:3] offset:64
	global_load_dword v223, v170, s[2:3] offset:-4032
	global_load_dword v233, v170, s[2:3] offset:64
	global_load_dword v248, v171, s[2:3] offset:-4032
	global_load_dword v0, v171, s[2:3] offset:64
	global_load_dword v1, v172, s[2:3] offset:-4032
	global_load_dword v2, v172, s[2:3] offset:64
	s_waitcnt vmcnt(31)
	v_add_f32_e32 v173, 1.0, v173
	v_add_f32_e32 v174, 1.0, v174
	v_add_f32_e32 v175, 1.0, v175
	v_add_f32_e32 v176, 1.0, v176
	v_mul_f32_e32 v173, 0.5, v173
	v_mul_f32_e32 v174, 0.5, v174
	v_mul_f32_e32 v175, 0.5, v175
	v_mul_f32_e32 v176, 0.5, v176
	v_sub_f32_e32 v50, v177, v132
	v_mul_f32_e32 v50, v50, v133
	v_fma_f32 v50, v3, v50, v19
	v_cndmask_b32_e64 v177, v177, v50, s[98:99]
	v_mul_f32_e32 v64, v64, v173
	v_fmac_f32_e32 v64, 0x3fb504f3, v177
	global_load_dword v177, v165, s[2:3] offset:-3968
	global_store_dword v165, v64, s[28:29] offset:-4096
	s_waitcnt vmcnt(32)
	v_sub_f32_e32 v50, v178, v134
	v_mul_f32_e32 v50, v50, v135
	v_fma_f32 v50, v3, v50, v19
	v_cndmask_b32_e64 v178, v178, v50, s[98:99]
	v_mul_f32_e32 v65, v65, v173
	v_fmac_f32_e32 v65, 0x3fb504f3, v178
	global_load_dword v178, v165, s[2:3] offset:128
	global_store_dword v165, v65, s[28:29] offset:0
	s_waitcnt vmcnt(33)
	v_sub_f32_e32 v50, v179, v136
	v_mul_f32_e32 v50, v50, v137
	v_fma_f32 v50, v3, v50, v19
	v_cndmask_b32_e64 v179, v179, v50, s[98:99]
	v_mul_f32_e32 v66, v66, v173
	v_fmac_f32_e32 v66, 0x3fb504f3, v179
	global_load_dword v179, v166, s[2:3] offset:-3968
	global_store_dword v166, v66, s[28:29] offset:-4096
	s_waitcnt vmcnt(34)
	v_sub_f32_e32 v50, v224, v138
	v_mul_f32_e32 v50, v50, v139
	v_fma_f32 v50, v3, v50, v19
	v_cndmask_b32_e64 v224, v224, v50, s[98:99]
	v_mul_f32_e32 v67, v67, v173
	v_fmac_f32_e32 v67, 0x3fb504f3, v224
	global_load_dword v224, v166, s[2:3] offset:128
	global_store_dword v166, v67, s[28:29] offset:0
	s_waitcnt vmcnt(35)
	v_sub_f32_e32 v50, v225, v140
	v_mul_f32_e32 v50, v50, v141
	v_fma_f32 v50, v3, v50, v19
	v_cndmask_b32_e64 v225, v225, v50, s[98:99]
	v_mul_f32_e32 v80, v80, v173
	v_fmac_f32_e32 v80, 0x3fb504f3, v225
	global_load_dword v225, v167, s[2:3] offset:-3968
	global_store_dword v167, v80, s[28:29] offset:-4096
	s_waitcnt vmcnt(36)
	v_sub_f32_e32 v50, v226, v142
	v_mul_f32_e32 v50, v50, v143
	v_fma_f32 v50, v3, v50, v19
	v_cndmask_b32_e64 v226, v226, v50, s[98:99]
	v_mul_f32_e32 v81, v81, v173
	v_fmac_f32_e32 v81, 0x3fb504f3, v226
	global_load_dword v226, v167, s[2:3] offset:128
	global_store_dword v167, v81, s[28:29] offset:0
	s_waitcnt vmcnt(37)
	v_sub_f32_e32 v50, v227, v144
	v_mul_f32_e32 v50, v50, v145
	v_fma_f32 v50, v3, v50, v19
	v_cndmask_b32_e64 v227, v227, v50, s[98:99]
	v_mul_f32_e32 v82, v82, v173
	v_fmac_f32_e32 v82, 0x3fb504f3, v227
	global_load_dword v227, v168, s[2:3] offset:-3968
	global_store_dword v168, v82, s[28:29] offset:-4096
	s_waitcnt vmcnt(38)
	v_sub_f32_e32 v50, v228, v146
	v_mul_f32_e32 v50, v50, v147
	v_fma_f32 v50, v3, v50, v19
	v_cndmask_b32_e64 v228, v228, v50, s[98:99]
	v_mul_f32_e32 v83, v83, v173
	v_fmac_f32_e32 v83, 0x3fb504f3, v228
	global_load_dword v228, v168, s[2:3] offset:128
	global_store_dword v168, v83, s[28:29] offset:0
	s_waitcnt vmcnt(39)
	v_sub_f32_e32 v50, v229, v148
	v_mul_f32_e32 v50, v50, v149
	v_fma_f32 v50, v3, v50, v19
	v_cndmask_b32_e64 v229, v229, v50, s[98:99]
	v_mul_f32_e32 v96, v96, v173
	v_fmac_f32_e32 v96, 0x3fb504f3, v229
	global_load_dword v229, v169, s[2:3] offset:-3968
	global_store_dword v169, v96, s[28:29] offset:-4096
	s_waitcnt vmcnt(40)
	v_sub_f32_e32 v50, v230, v150
	v_mul_f32_e32 v50, v50, v151
	v_fma_f32 v50, v3, v50, v19
	v_cndmask_b32_e64 v230, v230, v50, s[98:99]
	v_mul_f32_e32 v97, v97, v173
	v_fmac_f32_e32 v97, 0x3fb504f3, v230
	global_load_dword v230, v169, s[2:3] offset:128
	global_store_dword v169, v97, s[28:29] offset:0
	s_waitcnt vmcnt(41)
	v_sub_f32_e32 v50, v231, v152
	v_mul_f32_e32 v50, v50, v153
	v_fma_f32 v50, v3, v50, v19
	v_cndmask_b32_e64 v231, v231, v50, s[98:99]
	v_mul_f32_e32 v98, v98, v173
	v_fmac_f32_e32 v98, 0x3fb504f3, v231
	global_load_dword v231, v170, s[2:3] offset:-3968
	global_store_dword v170, v98, s[28:29] offset:-4096
	s_waitcnt vmcnt(42)
	v_sub_f32_e32 v50, v234, v154
	v_mul_f32_e32 v50, v50, v155
	v_fma_f32 v50, v3, v50, v19
	v_cndmask_b32_e64 v234, v234, v50, s[98:99]
	v_mul_f32_e32 v99, v99, v173
	v_fmac_f32_e32 v99, 0x3fb504f3, v234
	global_load_dword v234, v170, s[2:3] offset:128
	global_store_dword v170, v99, s[28:29] offset:0
	s_waitcnt vmcnt(43)
	v_sub_f32_e32 v50, v235, v156
	v_mul_f32_e32 v50, v50, v157
	v_fma_f32 v50, v3, v50, v19
	v_cndmask_b32_e64 v235, v235, v50, s[98:99]
	v_mul_f32_e32 v116, v116, v173
	v_fmac_f32_e32 v116, 0x3fb504f3, v235
	global_load_dword v235, v171, s[2:3] offset:-3968
	global_store_dword v171, v116, s[28:29] offset:-4096
	s_waitcnt vmcnt(44)
	v_sub_f32_e32 v50, v236, v158
	v_mul_f32_e32 v50, v50, v159
	v_fma_f32 v50, v3, v50, v19
	v_cndmask_b32_e64 v236, v236, v50, s[98:99]
	v_mul_f32_e32 v117, v117, v173
	v_fmac_f32_e32 v117, 0x3fb504f3, v236
	global_load_dword v236, v171, s[2:3] offset:128
	global_store_dword v171, v117, s[28:29] offset:0
	s_waitcnt vmcnt(45)
	v_sub_f32_e32 v50, v237, v160
	v_mul_f32_e32 v50, v50, v161
	v_fma_f32 v50, v3, v50, v19
	v_cndmask_b32_e64 v237, v237, v50, s[98:99]
	v_mul_f32_e32 v118, v118, v173
	v_fmac_f32_e32 v118, 0x3fb504f3, v237
	global_load_dword v237, v172, s[2:3] offset:-3968
	global_store_dword v172, v118, s[28:29] offset:-4096
	s_waitcnt vmcnt(46)
	v_sub_f32_e32 v50, v238, v162
	v_mul_f32_e32 v50, v50, v163
	v_fma_f32 v50, v3, v50, v19
	v_cndmask_b32_e64 v238, v238, v50, s[98:99]
	v_mul_f32_e32 v119, v119, v173
	v_fmac_f32_e32 v119, 0x3fb504f3, v238
	global_load_dword v238, v172, s[2:3] offset:128
	global_store_dword v172, v119, s[28:29] offset:0
	s_waitcnt vmcnt(47)
	v_sub_f32_e32 v50, v239, v132
	v_mul_f32_e32 v50, v50, v133
	v_fma_f32 v50, v16, v50, v32
	v_cndmask_b32_e64 v239, v239, v50, s[98:99]
	v_mul_f32_e32 v68, v68, v174
	v_fmac_f32_e32 v68, 0x3fb504f3, v239
	global_load_dword v239, v165, s[2:3] offset:-3904
	global_store_dword v165, v68, s[28:29] offset:-4032
	s_waitcnt vmcnt(48)
	v_sub_f32_e32 v50, v240, v134
	v_mul_f32_e32 v50, v50, v135
	v_fma_f32 v50, v16, v50, v32
	v_cndmask_b32_e64 v240, v240, v50, s[98:99]
	v_mul_f32_e32 v69, v69, v174
	v_fmac_f32_e32 v69, 0x3fb504f3, v240
	global_load_dword v240, v165, s[2:3] offset:192
	global_store_dword v165, v69, s[28:29] offset:64
	s_waitcnt vmcnt(49)
	v_sub_f32_e32 v50, v241, v136
	v_mul_f32_e32 v50, v50, v137
	v_fma_f32 v50, v16, v50, v32
	v_cndmask_b32_e64 v241, v241, v50, s[98:99]
	v_mul_f32_e32 v70, v70, v174
	v_fmac_f32_e32 v70, 0x3fb504f3, v241
	global_load_dword v241, v166, s[2:3] offset:-3904
	global_store_dword v166, v70, s[28:29] offset:-4032
	s_waitcnt vmcnt(50)
	v_sub_f32_e32 v50, v242, v138
	v_mul_f32_e32 v50, v50, v139
	v_fma_f32 v50, v16, v50, v32
	v_cndmask_b32_e64 v242, v242, v50, s[98:99]
	v_mul_f32_e32 v71, v71, v174
	v_fmac_f32_e32 v71, 0x3fb504f3, v242
	global_load_dword v242, v166, s[2:3] offset:192
	global_store_dword v166, v71, s[28:29] offset:64
	s_waitcnt vmcnt(51)
	v_sub_f32_e32 v50, v243, v140
	v_mul_f32_e32 v50, v50, v141
	v_fma_f32 v50, v16, v50, v32
	v_cndmask_b32_e64 v243, v243, v50, s[98:99]
	v_mul_f32_e32 v84, v84, v174
	v_fmac_f32_e32 v84, 0x3fb504f3, v243
	global_load_dword v243, v167, s[2:3] offset:-3904
	global_store_dword v167, v84, s[28:29] offset:-4032
	s_waitcnt vmcnt(52)
	v_sub_f32_e32 v50, v244, v142
	v_mul_f32_e32 v50, v50, v143
	v_fma_f32 v50, v16, v50, v32
	v_cndmask_b32_e64 v244, v244, v50, s[98:99]
	v_mul_f32_e32 v85, v85, v174
	v_fmac_f32_e32 v85, 0x3fb504f3, v244
	global_load_dword v244, v167, s[2:3] offset:192
	global_store_dword v167, v85, s[28:29] offset:64
	s_waitcnt vmcnt(53)
	v_sub_f32_e32 v50, v245, v144
	v_mul_f32_e32 v50, v50, v145
	v_fma_f32 v50, v16, v50, v32
	v_cndmask_b32_e64 v245, v245, v50, s[98:99]
	v_mul_f32_e32 v86, v86, v174
	v_fmac_f32_e32 v86, 0x3fb504f3, v245
	global_load_dword v245, v168, s[2:3] offset:-3904
	global_store_dword v168, v86, s[28:29] offset:-4032
	s_waitcnt vmcnt(54)
	v_sub_f32_e32 v50, v112, v146
	v_mul_f32_e32 v50, v50, v147
	v_fma_f32 v50, v16, v50, v32
	v_cndmask_b32_e64 v112, v112, v50, s[98:99]
	v_mul_f32_e32 v87, v87, v174
	v_fmac_f32_e32 v87, 0x3fb504f3, v112
	global_load_dword v112, v168, s[2:3] offset:192
	global_store_dword v168, v87, s[28:29] offset:64
	s_waitcnt vmcnt(55)
	v_sub_f32_e32 v50, v115, v148
	v_mul_f32_e32 v50, v50, v149
	v_fma_f32 v50, v16, v50, v32
	v_cndmask_b32_e64 v115, v115, v50, s[98:99]
	v_mul_f32_e32 v100, v100, v174
	v_fmac_f32_e32 v100, 0x3fb504f3, v115
	global_load_dword v115, v169, s[2:3] offset:-3904
	global_store_dword v169, v100, s[28:29] offset:-4032
	s_waitcnt vmcnt(56)
	v_sub_f32_e32 v50, v208, v150
	v_mul_f32_e32 v50, v50, v151
	v_fma_f32 v50, v16, v50, v32
	v_cndmask_b32_e64 v208, v208, v50, s[98:99]
	v_mul_f32_e32 v101, v101, v174
	v_fmac_f32_e32 v101, 0x3fb504f3, v208
	global_load_dword v208, v169, s[2:3] offset:192
	global_store_dword v169, v101, s[28:29] offset:64
	s_waitcnt vmcnt(57)
	v_sub_f32_e32 v50, v223, v152
	v_mul_f32_e32 v50, v50, v153
	v_fma_f32 v50, v16, v50, v32
	v_cndmask_b32_e64 v223, v223, v50, s[98:99]
	v_mul_f32_e32 v102, v102, v174
	v_fmac_f32_e32 v102, 0x3fb504f3, v223
	global_load_dword v223, v170, s[2:3] offset:-3904
	global_store_dword v170, v102, s[28:29] offset:-4032
	s_waitcnt vmcnt(58)
	v_sub_f32_e32 v50, v233, v154
	v_mul_f32_e32 v50, v50, v155
	v_fma_f32 v50, v16, v50, v32
	v_cndmask_b32_e64 v233, v233, v50, s[98:99]
	v_mul_f32_e32 v103, v103, v174
	v_fmac_f32_e32 v103, 0x3fb504f3, v233
	global_load_dword v233, v170, s[2:3] offset:192
	global_store_dword v170, v103, s[28:29] offset:64
	s_waitcnt vmcnt(59)
	v_sub_f32_e32 v50, v248, v156
	v_mul_f32_e32 v50, v50, v157
	v_fma_f32 v50, v16, v50, v32
	v_cndmask_b32_e64 v248, v248, v50, s[98:99]
	v_mul_f32_e32 v120, v120, v174
	v_fmac_f32_e32 v120, 0x3fb504f3, v248
	global_load_dword v248, v171, s[2:3] offset:-3904
	global_store_dword v171, v120, s[28:29] offset:-4032
	s_waitcnt vmcnt(60)
	v_sub_f32_e32 v50, v0, v158
	v_mul_f32_e32 v50, v50, v159
	v_fma_f32 v50, v16, v50, v32
	v_cndmask_b32_e64 v0, v0, v50, s[98:99]
	v_mul_f32_e32 v121, v121, v174
	v_fmac_f32_e32 v121, 0x3fb504f3, v0
	global_load_dword v0, v171, s[2:3] offset:192
	global_store_dword v171, v121, s[28:29] offset:64
	s_waitcnt vmcnt(61)
	v_sub_f32_e32 v50, v1, v160
	v_mul_f32_e32 v50, v50, v161
	v_fma_f32 v50, v16, v50, v32
	v_cndmask_b32_e64 v1, v1, v50, s[98:99]
	v_mul_f32_e32 v122, v122, v174
	v_fmac_f32_e32 v122, 0x3fb504f3, v1
	global_load_dword v1, v172, s[2:3] offset:-3904
	global_store_dword v172, v122, s[28:29] offset:-4032
	s_waitcnt vmcnt(62)
	v_sub_f32_e32 v50, v2, v162
	v_mul_f32_e32 v50, v50, v163
	v_fma_f32 v50, v16, v50, v32
	v_cndmask_b32_e64 v2, v2, v50, s[98:99]
	v_mul_f32_e32 v123, v123, v174
	v_fmac_f32_e32 v123, 0x3fb504f3, v2
	global_load_dword v2, v172, s[2:3] offset:192
	global_store_dword v172, v123, s[28:29] offset:64
	s_waitcnt vmcnt(63)
	v_sub_f32_e32 v50, v177, v132
	v_mul_f32_e32 v50, v50, v133
	v_fma_f32 v50, v17, v50, v33
	v_cndmask_b32_e64 v177, v177, v50, s[98:99]
	v_mul_f32_e32 v72, v72, v175
	v_fmac_f32_e32 v72, 0x3fb504f3, v177
	global_store_dword v165, v72, s[28:29] offset:-3968
	s_waitcnt vmcnt(62)
	v_sub_f32_e32 v50, v178, v134
	v_mul_f32_e32 v50, v50, v135
	v_fma_f32 v50, v17, v50, v33
	v_cndmask_b32_e64 v178, v178, v50, s[98:99]
	v_mul_f32_e32 v73, v73, v175
	v_fmac_f32_e32 v73, 0x3fb504f3, v178
	global_store_dword v165, v73, s[28:29] offset:128
	s_waitcnt vmcnt(61)
	v_sub_f32_e32 v50, v179, v136
	v_mul_f32_e32 v50, v50, v137
	v_fma_f32 v50, v17, v50, v33
	v_cndmask_b32_e64 v179, v179, v50, s[98:99]
	v_mul_f32_e32 v74, v74, v175
	v_fmac_f32_e32 v74, 0x3fb504f3, v179
	global_store_dword v166, v74, s[28:29] offset:-3968
	s_waitcnt vmcnt(60)
	v_sub_f32_e32 v50, v224, v138
	v_mul_f32_e32 v50, v50, v139
	v_fma_f32 v50, v17, v50, v33
	v_cndmask_b32_e64 v224, v224, v50, s[98:99]
	v_mul_f32_e32 v75, v75, v175
	v_fmac_f32_e32 v75, 0x3fb504f3, v224
	global_store_dword v166, v75, s[28:29] offset:128
	s_waitcnt vmcnt(59)
	v_sub_f32_e32 v50, v225, v140
	v_mul_f32_e32 v50, v50, v141
	v_fma_f32 v50, v17, v50, v33
	v_cndmask_b32_e64 v225, v225, v50, s[98:99]
	v_mul_f32_e32 v88, v88, v175
	v_fmac_f32_e32 v88, 0x3fb504f3, v225
	global_store_dword v167, v88, s[28:29] offset:-3968
	s_waitcnt vmcnt(58)
	v_sub_f32_e32 v50, v226, v142
	v_mul_f32_e32 v50, v50, v143
	v_fma_f32 v50, v17, v50, v33
	v_cndmask_b32_e64 v226, v226, v50, s[98:99]
	v_mul_f32_e32 v89, v89, v175
	v_fmac_f32_e32 v89, 0x3fb504f3, v226
	global_store_dword v167, v89, s[28:29] offset:128
	s_waitcnt vmcnt(57)
	v_sub_f32_e32 v50, v227, v144
	v_mul_f32_e32 v50, v50, v145
	v_fma_f32 v50, v17, v50, v33
	v_cndmask_b32_e64 v227, v227, v50, s[98:99]
	v_mul_f32_e32 v90, v90, v175
	v_fmac_f32_e32 v90, 0x3fb504f3, v227
	global_store_dword v168, v90, s[28:29] offset:-3968
	s_waitcnt vmcnt(56)
	v_sub_f32_e32 v50, v228, v146
	v_mul_f32_e32 v50, v50, v147
	v_fma_f32 v50, v17, v50, v33
	v_cndmask_b32_e64 v228, v228, v50, s[98:99]
	v_mul_f32_e32 v91, v91, v175
	v_fmac_f32_e32 v91, 0x3fb504f3, v228
	global_store_dword v168, v91, s[28:29] offset:128
	s_waitcnt vmcnt(55)
	v_sub_f32_e32 v50, v229, v148
	v_mul_f32_e32 v50, v50, v149
	v_fma_f32 v50, v17, v50, v33
	v_cndmask_b32_e64 v229, v229, v50, s[98:99]
	v_mul_f32_e32 v104, v104, v175
	v_fmac_f32_e32 v104, 0x3fb504f3, v229
	global_store_dword v169, v104, s[28:29] offset:-3968
	s_waitcnt vmcnt(54)
	v_sub_f32_e32 v50, v230, v150
	v_mul_f32_e32 v50, v50, v151
	v_fma_f32 v50, v17, v50, v33
	v_cndmask_b32_e64 v230, v230, v50, s[98:99]
	v_mul_f32_e32 v105, v105, v175
	v_fmac_f32_e32 v105, 0x3fb504f3, v230
	global_store_dword v169, v105, s[28:29] offset:128
	s_waitcnt vmcnt(53)
	v_sub_f32_e32 v50, v231, v152
	v_mul_f32_e32 v50, v50, v153
	v_fma_f32 v50, v17, v50, v33
	v_cndmask_b32_e64 v231, v231, v50, s[98:99]
	v_mul_f32_e32 v106, v106, v175
	v_fmac_f32_e32 v106, 0x3fb504f3, v231
	global_store_dword v170, v106, s[28:29] offset:-3968
	s_waitcnt vmcnt(52)
	v_sub_f32_e32 v50, v234, v154
	v_mul_f32_e32 v50, v50, v155
	v_fma_f32 v50, v17, v50, v33
	v_cndmask_b32_e64 v234, v234, v50, s[98:99]
	v_mul_f32_e32 v107, v107, v175
	v_fmac_f32_e32 v107, 0x3fb504f3, v234
	global_store_dword v170, v107, s[28:29] offset:128
	s_waitcnt vmcnt(51)
	v_sub_f32_e32 v50, v235, v156
	v_mul_f32_e32 v50, v50, v157
	v_fma_f32 v50, v17, v50, v33
	v_cndmask_b32_e64 v235, v235, v50, s[98:99]
	v_mul_f32_e32 v124, v124, v175
	v_fmac_f32_e32 v124, 0x3fb504f3, v235
	global_store_dword v171, v124, s[28:29] offset:-3968
	s_waitcnt vmcnt(50)
	v_sub_f32_e32 v50, v236, v158
	v_mul_f32_e32 v50, v50, v159
	v_fma_f32 v50, v17, v50, v33
	v_cndmask_b32_e64 v236, v236, v50, s[98:99]
	v_mul_f32_e32 v125, v125, v175
	v_fmac_f32_e32 v125, 0x3fb504f3, v236
	global_store_dword v171, v125, s[28:29] offset:128
	s_waitcnt vmcnt(49)
	v_sub_f32_e32 v50, v237, v160
	v_mul_f32_e32 v50, v50, v161
	v_fma_f32 v50, v17, v50, v33
	v_cndmask_b32_e64 v237, v237, v50, s[98:99]
	v_mul_f32_e32 v126, v126, v175
	v_fmac_f32_e32 v126, 0x3fb504f3, v237
	global_store_dword v172, v126, s[28:29] offset:-3968
	s_waitcnt vmcnt(48)
	v_sub_f32_e32 v50, v238, v162
	v_mul_f32_e32 v50, v50, v163
	v_fma_f32 v50, v17, v50, v33
	v_cndmask_b32_e64 v238, v238, v50, s[98:99]
	v_mul_f32_e32 v127, v127, v175
	v_fmac_f32_e32 v127, 0x3fb504f3, v238
	global_store_dword v172, v127, s[28:29] offset:128
	s_waitcnt vmcnt(47)
	v_sub_f32_e32 v50, v239, v132
	v_mul_f32_e32 v50, v50, v133
	v_fma_f32 v50, v18, v50, v34
	v_cndmask_b32_e64 v239, v239, v50, s[98:99]
	v_mul_f32_e32 v76, v76, v176
	v_fmac_f32_e32 v76, 0x3fb504f3, v239
	global_store_dword v165, v76, s[28:29] offset:-3904
	s_waitcnt vmcnt(46)
	v_sub_f32_e32 v50, v240, v134
	v_mul_f32_e32 v50, v50, v135
	v_fma_f32 v50, v18, v50, v34
	v_cndmask_b32_e64 v240, v240, v50, s[98:99]
	v_mul_f32_e32 v77, v77, v176
	v_fmac_f32_e32 v77, 0x3fb504f3, v240
	global_store_dword v165, v77, s[28:29] offset:192
	s_waitcnt vmcnt(45)
	v_sub_f32_e32 v50, v241, v136
	v_mul_f32_e32 v50, v50, v137
	v_fma_f32 v50, v18, v50, v34
	v_cndmask_b32_e64 v241, v241, v50, s[98:99]
	v_mul_f32_e32 v78, v78, v176
	v_fmac_f32_e32 v78, 0x3fb504f3, v241
	global_store_dword v166, v78, s[28:29] offset:-3904
	s_waitcnt vmcnt(44)
	v_sub_f32_e32 v50, v242, v138
	v_mul_f32_e32 v50, v50, v139
	v_fma_f32 v50, v18, v50, v34
	v_cndmask_b32_e64 v242, v242, v50, s[98:99]
	v_mul_f32_e32 v79, v79, v176
	v_fmac_f32_e32 v79, 0x3fb504f3, v242
	global_store_dword v166, v79, s[28:29] offset:192
	s_waitcnt vmcnt(43)
	v_sub_f32_e32 v50, v243, v140
	v_mul_f32_e32 v50, v50, v141
	v_fma_f32 v50, v18, v50, v34
	v_cndmask_b32_e64 v243, v243, v50, s[98:99]
	v_mul_f32_e32 v92, v92, v176
	v_fmac_f32_e32 v92, 0x3fb504f3, v243
	global_store_dword v167, v92, s[28:29] offset:-3904
	s_waitcnt vmcnt(42)
	v_sub_f32_e32 v50, v244, v142
	v_mul_f32_e32 v50, v50, v143
	v_fma_f32 v50, v18, v50, v34
	v_cndmask_b32_e64 v244, v244, v50, s[98:99]
	v_mul_f32_e32 v93, v93, v176
	v_fmac_f32_e32 v93, 0x3fb504f3, v244
	global_store_dword v167, v93, s[28:29] offset:192
	s_waitcnt vmcnt(41)
	v_sub_f32_e32 v50, v245, v144
	v_mul_f32_e32 v50, v50, v145
	v_fma_f32 v50, v18, v50, v34
	v_cndmask_b32_e64 v245, v245, v50, s[98:99]
	v_mul_f32_e32 v94, v94, v176
	v_fmac_f32_e32 v94, 0x3fb504f3, v245
	global_store_dword v168, v94, s[28:29] offset:-3904
	s_waitcnt vmcnt(40)
	v_sub_f32_e32 v50, v112, v146
	v_mul_f32_e32 v50, v50, v147
	v_fma_f32 v50, v18, v50, v34
	v_cndmask_b32_e64 v112, v112, v50, s[98:99]
	v_mul_f32_e32 v95, v95, v176
	v_fmac_f32_e32 v95, 0x3fb504f3, v112
	global_store_dword v168, v95, s[28:29] offset:192
	s_waitcnt vmcnt(39)
	v_sub_f32_e32 v50, v115, v148
	v_mul_f32_e32 v50, v50, v149
	v_fma_f32 v50, v18, v50, v34
	v_cndmask_b32_e64 v115, v115, v50, s[98:99]
	v_mul_f32_e32 v108, v108, v176
	v_fmac_f32_e32 v108, 0x3fb504f3, v115
	global_store_dword v169, v108, s[28:29] offset:-3904
	s_waitcnt vmcnt(38)
	v_sub_f32_e32 v50, v208, v150
	v_mul_f32_e32 v50, v50, v151
	v_fma_f32 v50, v18, v50, v34
	v_cndmask_b32_e64 v208, v208, v50, s[98:99]
	v_mul_f32_e32 v109, v109, v176
	v_fmac_f32_e32 v109, 0x3fb504f3, v208
	global_store_dword v169, v109, s[28:29] offset:192
	s_waitcnt vmcnt(37)
	v_sub_f32_e32 v50, v223, v152
	v_mul_f32_e32 v50, v50, v153
	v_fma_f32 v50, v18, v50, v34
	v_cndmask_b32_e64 v223, v223, v50, s[98:99]
	v_mul_f32_e32 v110, v110, v176
	v_fmac_f32_e32 v110, 0x3fb504f3, v223
	global_store_dword v170, v110, s[28:29] offset:-3904
	s_waitcnt vmcnt(36)
	v_sub_f32_e32 v50, v233, v154
	v_mul_f32_e32 v50, v50, v155
	v_fma_f32 v50, v18, v50, v34
	v_cndmask_b32_e64 v233, v233, v50, s[98:99]
	v_mul_f32_e32 v111, v111, v176
	v_fmac_f32_e32 v111, 0x3fb504f3, v233
	global_store_dword v170, v111, s[28:29] offset:192
	s_waitcnt vmcnt(35)
	v_sub_f32_e32 v50, v248, v156
	v_mul_f32_e32 v50, v50, v157
	v_fma_f32 v50, v18, v50, v34
	v_cndmask_b32_e64 v248, v248, v50, s[98:99]
	v_mul_f32_e32 v128, v128, v176
	v_fmac_f32_e32 v128, 0x3fb504f3, v248
	global_store_dword v171, v128, s[28:29] offset:-3904
	s_waitcnt vmcnt(34)
	v_sub_f32_e32 v50, v0, v158
	v_mul_f32_e32 v50, v50, v159
	v_fma_f32 v50, v18, v50, v34
	v_cndmask_b32_e64 v0, v0, v50, s[98:99]
	v_mul_f32_e32 v129, v129, v176
	v_fmac_f32_e32 v129, 0x3fb504f3, v0
	global_store_dword v171, v129, s[28:29] offset:192
	s_waitcnt vmcnt(33)
	v_sub_f32_e32 v50, v1, v160
	v_mul_f32_e32 v50, v50, v161
	v_fma_f32 v50, v18, v50, v34
	v_cndmask_b32_e64 v1, v1, v50, s[98:99]
	v_mul_f32_e32 v130, v130, v176
	v_fmac_f32_e32 v130, 0x3fb504f3, v1
	global_store_dword v172, v130, s[28:29] offset:-3904
	s_waitcnt vmcnt(32)
	v_sub_f32_e32 v50, v2, v162
	v_mul_f32_e32 v50, v50, v163
	v_fma_f32 v50, v18, v50, v34
	v_cndmask_b32_e64 v2, v2, v50, s[98:99]
	v_mul_f32_e32 v131, v131, v176
	v_fmac_f32_e32 v131, 0x3fb504f3, v2
	global_store_dword v172, v131, s[28:29] offset:192
	s_add_i32 s13, s13, s59
	s_cmpk_gt_i32 s13, 0x3ff
	s_cbranch_scc0 .LBB0_153
	v_mov_b32_e32 v113, 0
	v_mov_b32_e32 v114, 0x3f317218

.LBB0_649:
	s_waitcnt lgkmcnt(0)
	s_lshr_b32 s0, s11, 6
	s_lshl_b32 s0, s0, 3
	s_and_b32 s4, s11, 7
	s_or_b32 s0, s0, s4
	s_lshl_b32 s0, s0, 8
	s_bfe_u32 s14, s11, 0x30003
	s_lshl_b32 s14, s14, 7
	v_lshrrev_b32_e32 v132, 4, v182
	v_xor_b32_e32 v132, v132, v182
	v_and_b32_e32 v132, 7, v132
	v_lshlrev_b32_e32 v132, 4, v132
	v_lshrrev_b32_e32 v133, 3, v182
	v_lshrrev_b32_e32 v134, 6, v182
	v_mul_u32_u24_e32 v180, 0x1600, v133
	v_readfirstlane_b32 s5, v134
	v_add_u32_e32 v180, v180, v132
	v_and_b32_e32 v135, 15, v182
	v_bfe_u32 v136, v182, 4, 2
	v_bfe_u32 v137, v182, 1, 3
	v_xor_b32_e32 v138, v136, v137
	v_or_b32_e32 v139, 4, v136
	v_xor_b32_e32 v139, v139, v137
	v_lshlrev_b32_e32 v138, 4, v138
	v_lshlrev_b32_e32 v139, 4, v139
	v_lshl_or_b32 v138, v135, 7, v138
	v_lshl_or_b32 v139, v135, 7, v139
	v_bfe_u32 v140, v182, 7, 1
	v_bfe_u32 v141, v182, 6, 1
	v_lshl_add_u32 v181, v140, 14, v138
	v_lshl_add_u32 v208, v140, 14, v139
	v_lshl_add_u32 v223, v141, 13, v138
	v_lshl_add_u32 v233, v141, 13, v139
	s_lshl_b32 s5, s5, 10
	s_mul_hi_u32 s15, s0, 0x1600
	s_mul_i32 s4, s0, 0x1600
	s_add_u32 s8, s30, s4
	s_addc_u32 s9, s31, s15
	s_mul_hi_u32 s15, s14, 0x1600
	s_mul_i32 s4, s14, 0x1600
	v_readlane_b32 s12, v250, 19
	v_readlane_b32 s13, v250, 20
	s_add_u32 s12, s12, s4
	s_addc_u32 s13, s13, s15
	s_mov_b32 s23, 0x8000
	s_add_u32 m0, s5, 0x0
	s_nop 0
	global_load_lds_dwordx4 v180, s[8:9]
	s_add_u32 m0, s5, 0x1000
	s_add_u32 s20, s8, 0x2c000
	s_addc_u32 s21, s9, 0
	global_load_lds_dwordx4 v180, s[20:21]
	s_add_u32 m0, s5, 0x2000
	s_add_u32 s20, s8, 0x58000
	s_addc_u32 s21, s9, 0
	global_load_lds_dwordx4 v180, s[20:21]
	s_add_u32 m0, s5, 0x3000
	s_add_u32 s20, s8, 0x84000
	s_addc_u32 s21, s9, 0
	global_load_lds_dwordx4 v180, s[20:21]
	s_add_u32 m0, s5, 0x4000
	s_add_u32 s20, s8, 0xb0000
	s_addc_u32 s21, s9, 0
	global_load_lds_dwordx4 v180, s[20:21]
	s_add_u32 m0, s5, 0x5000
	s_add_u32 s20, s8, 0xdc000
	s_addc_u32 s21, s9, 0
	global_load_lds_dwordx4 v180, s[20:21]
	s_add_u32 m0, s5, 0x6000
	s_add_u32 s20, s8, 0x108000
	s_addc_u32 s21, s9, 0
	global_load_lds_dwordx4 v180, s[20:21]
	s_add_u32 m0, s5, 0x7000
	s_add_u32 s20, s8, 0x134000
	s_addc_u32 s21, s9, 0
	global_load_lds_dwordx4 v180, s[20:21]
	s_add_u32 s8, s8, 0x80
	s_addc_u32 s9, s9, 0
	s_add_u32 m0, s5, s23
	s_nop 0
	global_load_lds_dwordx4 v180, s[12:13]
	s_add_u32 m0, m0, 0x1000
	s_add_u32 s20, s12, 0x2c000
	s_addc_u32 s21, s13, 0
	global_load_lds_dwordx4 v180, s[20:21]
	s_add_u32 m0, m0, 0x1000
	s_add_u32 s20, s12, 0x58000
	s_addc_u32 s21, s13, 0
	global_load_lds_dwordx4 v180, s[20:21]
	s_add_u32 m0, m0, 0x1000
	s_add_u32 s20, s12, 0x84000
	s_addc_u32 s21, s13, 0
	global_load_lds_dwordx4 v180, s[20:21]
	s_add_u32 s12, s12, 0x80
	s_addc_u32 s13, s13, 0
	v_mov_b32_e32 v0, 0
	v_mov_b32_e32 v1, v0
	v_mov_b32_e32 v2, v0
	v_mov_b32_e32 v3, v0
	v_mov_b32_e32 v4, v0
	v_mov_b32_e32 v5, v0
	v_mov_b32_e32 v6, v0
	v_mov_b32_e32 v7, v0
	v_mov_b32_e32 v8, v0
	v_mov_b32_e32 v9, v0
	v_mov_b32_e32 v10, v0
	v_mov_b32_e32 v11, v0
	v_mov_b32_e32 v12, v0
	v_mov_b32_e32 v13, v0
	v_mov_b32_e32 v14, v0
	v_mov_b32_e32 v15, v0
	v_mov_b32_e32 v16, v0
	v_mov_b32_e32 v17, v0
	v_mov_b32_e32 v18, v0
	v_mov_b32_e32 v19, v0
	v_mov_b32_e32 v20, v0
	v_mov_b32_e32 v21, v0
	v_mov_b32_e32 v22, v0
	v_mov_b32_e32 v23, v0
	v_mov_b32_e32 v24, v0
	v_mov_b32_e32 v25, v0
	v_mov_b32_e32 v26, v0
	v_mov_b32_e32 v27, v0
	v_mov_b32_e32 v28, v0
	v_mov_b32_e32 v29, v0
	v_mov_b32_e32 v30, v0
	v_mov_b32_e32 v31, v0
	v_mov_b32_e32 v32, v0
	v_mov_b32_e32 v33, v0
	v_mov_b32_e32 v34, v0
	v_mov_b32_e32 v35, v0
	v_mov_b32_e32 v36, v0
	v_mov_b32_e32 v37, v0
	v_mov_b32_e32 v38, v0
	v_mov_b32_e32 v39, v0
	v_mov_b32_e32 v40, v0
	v_mov_b32_e32 v41, v0
	v_mov_b32_e32 v42, v0
	v_mov_b32_e32 v43, v0
	v_mov_b32_e32 v44, v0
	v_mov_b32_e32 v45, v0
	v_mov_b32_e32 v46, v0
	v_mov_b32_e32 v47, v0
	v_mov_b32_e32 v48, v0
	v_mov_b32_e32 v49, v0
	v_mov_b32_e32 v50, v0
	v_mov_b32_e32 v51, v0
	v_mov_b32_e32 v52, v0
	v_mov_b32_e32 v53, v0
	v_mov_b32_e32 v54, v0
	v_mov_b32_e32 v55, v0
	v_mov_b32_e32 v56, v0
	v_mov_b32_e32 v57, v0
	v_mov_b32_e32 v58, v0
	v_mov_b32_e32 v59, v0
	v_mov_b32_e32 v60, v0
	v_mov_b32_e32 v61, v0
	v_mov_b32_e32 v62, v0
	v_mov_b32_e32 v63, v0
	v_mov_b32_e32 v64, v0
	v_mov_b32_e32 v65, v0
	v_mov_b32_e32 v66, v0
	v_mov_b32_e32 v67, v0
	v_mov_b32_e32 v68, v0
	v_mov_b32_e32 v69, v0
	v_mov_b32_e32 v70, v0
	v_mov_b32_e32 v71, v0
	v_mov_b32_e32 v72, v0
	v_mov_b32_e32 v73, v0
	v_mov_b32_e32 v74, v0
	v_mov_b32_e32 v75, v0
	v_mov_b32_e32 v76, v0
	v_mov_b32_e32 v77, v0
	v_mov_b32_e32 v78, v0
	v_mov_b32_e32 v79, v0
	v_mov_b32_e32 v80, v0
	v_mov_b32_e32 v81, v0
	v_mov_b32_e32 v82, v0
	v_mov_b32_e32 v83, v0
	v_mov_b32_e32 v84, v0
	v_mov_b32_e32 v85, v0
	v_mov_b32_e32 v86, v0
	v_mov_b32_e32 v87, v0
	v_mov_b32_e32 v88, v0
	v_mov_b32_e32 v89, v0
	v_mov_b32_e32 v90, v0
	v_mov_b32_e32 v91, v0
	v_mov_b32_e32 v92, v0
	v_mov_b32_e32 v93, v0
	v_mov_b32_e32 v94, v0
	v_mov_b32_e32 v95, v0
	v_mov_b32_e32 v96, v0
	v_mov_b32_e32 v97, v0
	v_mov_b32_e32 v98, v0
	v_mov_b32_e32 v99, v0
	v_mov_b32_e32 v100, v0
	v_mov_b32_e32 v101, v0
	v_mov_b32_e32 v102, v0
	v_mov_b32_e32 v103, v0
	v_mov_b32_e32 v104, v0
	v_mov_b32_e32 v105, v0
	v_mov_b32_e32 v106, v0
	v_mov_b32_e32 v107, v0
	v_mov_b32_e32 v108, v0
	v_mov_b32_e32 v109, v0
	v_mov_b32_e32 v110, v0
	v_mov_b32_e32 v111, v0
	v_mov_b32_e32 v116, v0
	v_mov_b32_e32 v117, v0
	v_mov_b32_e32 v118, v0
	v_mov_b32_e32 v119, v0
	v_mov_b32_e32 v120, v0
	v_mov_b32_e32 v121, v0
	v_mov_b32_e32 v122, v0
	v_mov_b32_e32 v123, v0
	v_mov_b32_e32 v124, v0
	v_mov_b32_e32 v125, v0
	v_mov_b32_e32 v126, v0
	v_mov_b32_e32 v127, v0
	v_mov_b32_e32 v128, v0
	v_mov_b32_e32 v129, v0
	v_mov_b32_e32 v130, v0
	v_mov_b32_e32 v131, v0
	s_movk_i32 s16, 43
.Lg4_r3:
	s_waitcnt vmcnt(0)
	s_barrier
	s_xor_b32 s23, s23, 0x4000
	s_cmp_eq_u32 s16, 0
	s_cbranch_scc1 .Lg4_r3_nb
	s_add_u32 m0, s5, s23
	s_nop 0
	global_load_lds_dwordx4 v180, s[12:13]
	s_add_u32 m0, m0, 0x1000
	s_add_u32 s20, s12, 0x2c000
	s_addc_u32 s21, s13, 0
	global_load_lds_dwordx4 v180, s[20:21]
	s_add_u32 m0, m0, 0x1000
	s_add_u32 s20, s12, 0x58000
	s_addc_u32 s21, s13, 0
	global_load_lds_dwordx4 v180, s[20:21]
	s_add_u32 m0, m0, 0x1000
	s_add_u32 s20, s12, 0x84000
	s_addc_u32 s21, s13, 0
	global_load_lds_dwordx4 v180, s[20:21]
	s_add_u32 s12, s12, 0x80
	s_addc_u32 s13, s13, 0

.Lg4_r3_nl:
	s_waitcnt lgkmcnt(1)
	v_mfma_f32_16x16x32_f16 v[0:3], v[132:135], v[242:245], v[0:3]
	v_mfma_f32_16x16x32_f16 v[16:19], v[136:139], v[242:245], v[16:19]
	v_mfma_f32_16x16x32_f16 v[32:35], v[140:143], v[242:245], v[32:35]
	v_mfma_f32_16x16x32_f16 v[48:51], v[144:147], v[242:245], v[48:51]
	v_mfma_f32_16x16x32_f16 v[64:67], v[148:151], v[242:245], v[64:67]
	v_mfma_f32_16x16x32_f16 v[80:83], v[152:155], v[242:245], v[80:83]
	v_mfma_f32_16x16x32_f16 v[96:99], v[156:159], v[242:245], v[96:99]
	v_mfma_f32_16x16x32_f16 v[116:119], v[160:163], v[242:245], v[116:119]
	ds_read_b128 v[242:245], v223 offset:36864
	s_waitcnt lgkmcnt(1)
	v_mfma_f32_16x16x32_f16 v[4:7], v[132:135], v[112:115], v[4:7]
	v_mfma_f32_16x16x32_f16 v[20:23], v[136:139], v[112:115], v[20:23]
	v_mfma_f32_16x16x32_f16 v[36:39], v[140:143], v[112:115], v[36:39]
	v_mfma_f32_16x16x32_f16 v[52:55], v[144:147], v[112:115], v[52:55]
	v_mfma_f32_16x16x32_f16 v[68:71], v[148:151], v[112:115], v[68:71]
	v_mfma_f32_16x16x32_f16 v[84:87], v[152:155], v[112:115], v[84:87]
	v_mfma_f32_16x16x32_f16 v[100:103], v[156:159], v[112:115], v[100:103]
	v_mfma_f32_16x16x32_f16 v[120:123], v[160:163], v[112:115], v[120:123]
	ds_read_b128 v[112:115], v223 offset:38912
	s_waitcnt lgkmcnt(1)
	v_mfma_f32_16x16x32_f16 v[8:11], v[132:135], v[242:245], v[8:11]
	v_mfma_f32_16x16x32_f16 v[24:27], v[136:139], v[242:245], v[24:27]
	v_mfma_f32_16x16x32_f16 v[40:43], v[140:143], v[242:245], v[40:43]
	v_mfma_f32_16x16x32_f16 v[56:59], v[144:147], v[242:245], v[56:59]
	v_mfma_f32_16x16x32_f16 v[72:75], v[148:151], v[242:245], v[72:75]
	v_mfma_f32_16x16x32_f16 v[88:91], v[152:155], v[242:245], v[88:91]
	v_mfma_f32_16x16x32_f16 v[104:107], v[156:159], v[242:245], v[104:107]
	v_mfma_f32_16x16x32_f16 v[124:127], v[160:163], v[242:245], v[124:127]
	ds_read_b128 v[242:245], v233 offset:32768
	s_waitcnt lgkmcnt(1)
	v_mfma_f32_16x16x32_f16 v[12:15], v[132:135], v[112:115], v[12:15]
	v_mfma_f32_16x16x32_f16 v[28:31], v[136:139], v[112:115], v[28:31]
	v_mfma_f32_16x16x32_f16 v[44:47], v[140:143], v[112:115], v[44:47]
	v_mfma_f32_16x16x32_f16 v[60:63], v[144:147], v[112:115], v[60:63]
	v_mfma_f32_16x16x32_f16 v[76:79], v[148:151], v[112:115], v[76:79]
	v_mfma_f32_16x16x32_f16 v[92:95], v[152:155], v[112:115], v[92:95]
	v_mfma_f32_16x16x32_f16 v[108:111], v[156:159], v[112:115], v[108:111]
	v_mfma_f32_16x16x32_f16 v[128:131], v[160:163], v[112:115], v[128:131]
	ds_read_b128 v[112:115], v233 offset:34816
	s_waitcnt lgkmcnt(1)
	v_mfma_f32_16x16x32_f16 v[0:3], v[164:167], v[242:245], v[0:3]
	v_mfma_f32_16x16x32_f16 v[16:19], v[168:171], v[242:245], v[16:19]
	v_mfma_f32_16x16x32_f16 v[32:35], v[172:175], v[242:245], v[32:35]
	v_mfma_f32_16x16x32_f16 v[48:51], v[176:179], v[242:245], v[48:51]
	v_mfma_f32_16x16x32_f16 v[64:67], v[224:227], v[242:245], v[64:67]
	v_mfma_f32_16x16x32_f16 v[80:83], v[228:231], v[242:245], v[80:83]
	v_mfma_f32_16x16x32_f16 v[96:99], v[234:237], v[242:245], v[96:99]
	v_mfma_f32_16x16x32_f16 v[116:119], v[238:241], v[242:245], v[116:119]
	ds_read_b128 v[242:245], v233 offset:36864
	s_waitcnt lgkmcnt(1)
	v_mfma_f32_16x16x32_f16 v[4:7], v[164:167], v[112:115], v[4:7]
	v_mfma_f32_16x16x32_f16 v[20:23], v[168:171], v[112:115], v[20:23]
	v_mfma_f32_16x16x32_f16 v[36:39], v[172:175], v[112:115], v[36:39]
	v_mfma_f32_16x16x32_f16 v[52:55], v[176:179], v[112:115], v[52:55]
	v_mfma_f32_16x16x32_f16 v[68:71], v[224:227], v[112:115], v[68:71]
	v_mfma_f32_16x16x32_f16 v[84:87], v[228:231], v[112:115], v[84:87]
	v_mfma_f32_16x16x32_f16 v[100:103], v[234:237], v[112:115], v[100:103]
	v_mfma_f32_16x16x32_f16 v[120:123], v[238:241], v[112:115], v[120:123]
	ds_read_b128 v[112:115], v233 offset:38912
	s_waitcnt lgkmcnt(1)
	v_mfma_f32_16x16x32_f16 v[8:11], v[164:167], v[242:245], v[8:11]
	v_mfma_f32_16x16x32_f16 v[24:27], v[168:171], v[242:245], v[24:27]
	v_mfma_f32_16x16x32_f16 v[40:43], v[172:175], v[242:245], v[40:43]
	v_mfma_f32_16x16x32_f16 v[56:59], v[176:179], v[242:245], v[56:59]
	v_mfma_f32_16x16x32_f16 v[72:75], v[224:227], v[242:245], v[72:75]
	v_mfma_f32_16x16x32_f16 v[88:91], v[228:231], v[242:245], v[88:91]
	v_mfma_f32_16x16x32_f16 v[104:107], v[234:237], v[242:245], v[104:107]
	v_mfma_f32_16x16x32_f16 v[124:127], v[238:241], v[242:245], v[124:127]
	s_waitcnt lgkmcnt(0)
	v_mfma_f32_16x16x32_f16 v[12:15], v[164:167], v[112:115], v[12:15]
	v_mfma_f32_16x16x32_f16 v[28:31], v[168:171], v[112:115], v[28:31]
	v_mfma_f32_16x16x32_f16 v[44:47], v[172:175], v[112:115], v[44:47]
	v_mfma_f32_16x16x32_f16 v[60:63], v[176:179], v[112:115], v[60:63]
	v_mfma_f32_16x16x32_f16 v[76:79], v[224:227], v[112:115], v[76:79]
	v_mfma_f32_16x16x32_f16 v[92:95], v[228:231], v[112:115], v[92:95]
	v_mfma_f32_16x16x32_f16 v[108:111], v[234:237], v[112:115], v[108:111]
	v_mfma_f32_16x16x32_f16 v[128:131], v[238:241], v[112:115], v[128:131]
	v_xor_b32_e32 v223, 0x4000, v223
	v_xor_b32_e32 v233, 0x4000, v233
	s_sub_u32 s16, s16, 1
	s_cmp_lg_u32 s16, -1
	s_cbranch_scc1 .Lg4_r3
	s_nop 7
	v_bfe_u32 v208, v182, 7, 1
	v_bfe_u32 v223, v182, 4, 2
	v_lshlrev_b32_e32 v223, 2, v223
	v_lshl_or_b32 v208, v208, 7, v223
	v_add_u32_e32 v180, s0, v208
	v_bfe_u32 v208, v182, 6, 1
	v_and_b32_e32 v223, 15, v182
	v_lshl_or_b32 v208, v208, 6, v223
	v_add_u32_e32 v208, s14, v208
	v_lshlrev_b32_e32 v181, 2, v208
	s_lshr_b32 s4, s0, 13
	s_add_i32 s4, s4, s10
	s_mul_hi_i32 s9, s4, 0x9000
	s_mul_i32 s8, s4, 0x9000
	s_add_u32 s8, s50, s8
	s_addc_u32 s9, s51, s9
	s_add_u32 s8, s8, 0x8000
	s_addc_u32 s9, s9, 0
	v_mov_b32_e32 v247, s9
	v_add_co_u32_e32 v246, vcc, s8, v181
	v_addc_co_u32_e32 v247, vcc, 0, v247, vcc
	v_lshl_add_u32 v164, v180, 12, v181
	v_add_u32_e32 v165, 0x1000, v164
	v_add_u32_e32 v166, 0x3000, v164
	v_add_u32_e32 v167, 0x11000, v164
	v_add_u32_e32 v168, 0x13000, v164
	v_add_u32_e32 v169, 0x21000, v164
	v_add_u32_e32 v170, 0x23000, v164
	v_add_u32_e32 v171, 0x31000, v164
	v_add_u32_e32 v172, 0x33000, v164
	v_lshlrev_b32_e32 v115, 3, v180
	v_add_u32_e32 v115, 0x1e200000, v115
	v_mov_b32_e32 v223, s71
	v_mul_u32_u24_e32 v223, 3, v223
	v_add_u32_e32 v223, 1, v223
	v_lshl_add_u32 v208, v223, 12, v181
	global_load_dwordx2 v[132:133], v115, s[30:31] offset:0
	global_load_dwordx2 v[134:135], v115, s[30:31] offset:8
	global_load_dwordx2 v[136:137], v115, s[30:31] offset:16
	global_load_dwordx2 v[138:139], v115, s[30:31] offset:24
	global_load_dwordx2 v[140:141], v115, s[30:31] offset:128
	global_load_dwordx2 v[142:143], v115, s[30:31] offset:136
	global_load_dwordx2 v[144:145], v115, s[30:31] offset:144
	global_load_dwordx2 v[146:147], v115, s[30:31] offset:152
	global_load_dwordx2 v[148:149], v115, s[30:31] offset:256
	global_load_dwordx2 v[150:151], v115, s[30:31] offset:264
	global_load_dwordx2 v[152:153], v115, s[30:31] offset:272
	global_load_dwordx2 v[154:155], v115, s[30:31] offset:280
	global_load_dwordx2 v[156:157], v115, s[30:31] offset:384
	global_load_dwordx2 v[158:159], v115, s[30:31] offset:392
	global_load_dwordx2 v[160:161], v115, s[30:31] offset:400
	global_load_dwordx2 v[162:163], v115, s[30:31] offset:408
	global_load_dword v239, v208, s[24:25] offset:0
	global_load_dword v243, v208, s[26:27] offset:0
	global_load_dword v240, v208, s[24:25] offset:64
	global_load_dword v244, v208, s[26:27] offset:64
	global_load_dword v241, v208, s[24:25] offset:128
	global_load_dword v245, v208, s[26:27] offset:128
	global_load_dword v242, v208, s[24:25] offset:192
	global_load_dword v112, v208, s[26:27] offset:192
	global_load_dword v173, v[246:247], off offset:0
	global_load_dword v174, v[246:247], off offset:64
	global_load_dword v175, v[246:247], off offset:128
	global_load_dword v176, v[246:247], off offset:192
	global_load_dword v177, v165, s[28:29] offset:-4096
	global_load_dword v178, v165, s[28:29] offset:0
	global_load_dword v179, v166, s[28:29] offset:-4096
	global_load_dword v224, v166, s[28:29] offset:0
	global_load_dword v225, v167, s[28:29] offset:-4096
	global_load_dword v226, v167, s[28:29] offset:0
	global_load_dword v227, v168, s[28:29] offset:-4096
	global_load_dword v228, v168, s[28:29] offset:0
	global_load_dword v229, v169, s[28:29] offset:-4096
	global_load_dword v230, v169, s[28:29] offset:0
	global_load_dword v231, v170, s[28:29] offset:-4096
	global_load_dword v234, v170, s[28:29] offset:0
	global_load_dword v235, v171, s[28:29] offset:-4096
	global_load_dword v236, v171, s[28:29] offset:0
	global_load_dword v237, v172, s[28:29] offset:-4096
	global_load_dword v238, v172, s[28:29] offset:0
	s_waitcnt vmcnt(15)
	v_add_f32_e32 v173, 1.0, v173
	v_add_f32_e32 v174, 1.0, v174
	v_add_f32_e32 v175, 1.0, v175
	v_add_f32_e32 v176, 1.0, v176
	v_mul_f32_e32 v173, 0.5, v173
	v_mul_f32_e32 v174, 0.5, v174
	v_mul_f32_e32 v175, 0.5, v175
	v_mul_f32_e32 v176, 0.5, v176
	v_sub_f32_e32 v177, v177, v132
	v_mul_f32_e32 v177, v177, v133
	v_fma_f32 v177, v239, v177, v243
	v_mul_f32_e32 v0, v0, v173
	v_fmac_f32_e32 v0, 0x3fb504f3, v177
	global_load_dword v177, v165, s[28:29] offset:-4032
	global_store_dword v165, v0, s[28:29] offset:-4096
	s_waitcnt vmcnt(16)
	v_sub_f32_e32 v178, v178, v134
	v_mul_f32_e32 v178, v178, v135
	v_fma_f32 v178, v239, v178, v243
	v_mul_f32_e32 v1, v1, v173
	v_fmac_f32_e32 v1, 0x3fb504f3, v178
	global_load_dword v178, v165, s[28:29] offset:64
	global_store_dword v165, v1, s[28:29] offset:0
	s_waitcnt vmcnt(17)
	v_sub_f32_e32 v179, v179, v136
	v_mul_f32_e32 v179, v179, v137
	v_fma_f32 v179, v239, v179, v243
	v_mul_f32_e32 v2, v2, v173
	v_fmac_f32_e32 v2, 0x3fb504f3, v179
	global_load_dword v179, v166, s[28:29] offset:-4032
	global_store_dword v166, v2, s[28:29] offset:-4096
	s_waitcnt vmcnt(18)
	v_sub_f32_e32 v224, v224, v138
	v_mul_f32_e32 v224, v224, v139
	v_fma_f32 v224, v239, v224, v243
	v_mul_f32_e32 v3, v3, v173
	v_fmac_f32_e32 v3, 0x3fb504f3, v224
	global_load_dword v224, v166, s[28:29] offset:64
	global_store_dword v166, v3, s[28:29] offset:0
	s_waitcnt vmcnt(19)
	v_sub_f32_e32 v225, v225, v140
	v_mul_f32_e32 v225, v225, v141
	v_fma_f32 v225, v239, v225, v243
	v_mul_f32_e32 v16, v16, v173
	v_fmac_f32_e32 v16, 0x3fb504f3, v225
	global_load_dword v225, v167, s[28:29] offset:-4032
	global_store_dword v167, v16, s[28:29] offset:-4096
	s_waitcnt vmcnt(20)
	v_sub_f32_e32 v226, v226, v142
	v_mul_f32_e32 v226, v226, v143
	v_fma_f32 v226, v239, v226, v243
	v_mul_f32_e32 v17, v17, v173
	v_fmac_f32_e32 v17, 0x3fb504f3, v226
	global_load_dword v226, v167, s[28:29] offset:64
	global_store_dword v167, v17, s[28:29] offset:0
	s_waitcnt vmcnt(21)
	v_sub_f32_e32 v227, v227, v144
	v_mul_f32_e32 v227, v227, v145
	v_fma_f32 v227, v239, v227, v243
	v_mul_f32_e32 v18, v18, v173
	v_fmac_f32_e32 v18, 0x3fb504f3, v227
	global_load_dword v227, v168, s[28:29] offset:-4032
	global_store_dword v168, v18, s[28:29] offset:-4096
	s_waitcnt vmcnt(22)
	v_sub_f32_e32 v228, v228, v146
	v_mul_f32_e32 v228, v228, v147
	v_fma_f32 v228, v239, v228, v243
	v_mul_f32_e32 v19, v19, v173
	v_fmac_f32_e32 v19, 0x3fb504f3, v228
	global_load_dword v228, v168, s[28:29] offset:64
	global_store_dword v168, v19, s[28:29] offset:0
	s_waitcnt vmcnt(23)
	v_sub_f32_e32 v229, v229, v148
	v_mul_f32_e32 v229, v229, v149
	v_fma_f32 v229, v239, v229, v243
	v_mul_f32_e32 v32, v32, v173
	v_fmac_f32_e32 v32, 0x3fb504f3, v229
	global_load_dword v229, v169, s[28:29] offset:-4032
	global_store_dword v169, v32, s[28:29] offset:-4096
	s_waitcnt vmcnt(24)
	v_sub_f32_e32 v230, v230, v150
	v_mul_f32_e32 v230, v230, v151
	v_fma_f32 v230, v239, v230, v243
	v_mul_f32_e32 v33, v33, v173
	v_fmac_f32_e32 v33, 0x3fb504f3, v230
	global_load_dword v230, v169, s[28:29] offset:64
	global_store_dword v169, v33, s[28:29] offset:0
	s_waitcnt vmcnt(25)
	v_sub_f32_e32 v231, v231, v152
	v_mul_f32_e32 v231, v231, v153
	v_fma_f32 v231, v239, v231, v243
	v_mul_f32_e32 v34, v34, v173
	v_fmac_f32_e32 v34, 0x3fb504f3, v231
	global_load_dword v231, v170, s[28:29] offset:-4032
	global_store_dword v170, v34, s[28:29] offset:-4096
	s_waitcnt vmcnt(26)
	v_sub_f32_e32 v234, v234, v154
	v_mul_f32_e32 v234, v234, v155
	v_fma_f32 v234, v239, v234, v243
	v_mul_f32_e32 v35, v35, v173
	v_fmac_f32_e32 v35, 0x3fb504f3, v234
	global_load_dword v234, v170, s[28:29] offset:64
	global_store_dword v170, v35, s[28:29] offset:0
	s_waitcnt vmcnt(27)
	v_sub_f32_e32 v235, v235, v156
	v_mul_f32_e32 v235, v235, v157
	v_fma_f32 v235, v239, v235, v243
	v_mul_f32_e32 v48, v48, v173
	v_fmac_f32_e32 v48, 0x3fb504f3, v235
	global_load_dword v235, v171, s[28:29] offset:-4032
	global_store_dword v171, v48, s[28:29] offset:-4096
	s_waitcnt vmcnt(28)
	v_sub_f32_e32 v236, v236, v158
	v_mul_f32_e32 v236, v236, v159
	v_fma_f32 v236, v239, v236, v243
	v_mul_f32_e32 v49, v49, v173
	v_fmac_f32_e32 v49, 0x3fb504f3, v236
	global_load_dword v236, v171, s[28:29] offset:64
	global_store_dword v171, v49, s[28:29] offset:0
	s_waitcnt vmcnt(29)
	v_sub_f32_e32 v237, v237, v160
	v_mul_f32_e32 v237, v237, v161
	v_fma_f32 v237, v239, v237, v243
	v_mul_f32_e32 v50, v50, v173
	v_fmac_f32_e32 v50, 0x3fb504f3, v237
	global_load_dword v237, v172, s[28:29] offset:-4032
	global_store_dword v172, v50, s[28:29] offset:-4096
	s_waitcnt vmcnt(30)
	v_sub_f32_e32 v238, v238, v162
	v_mul_f32_e32 v238, v238, v163
	v_fma_f32 v238, v239, v238, v243
	v_mul_f32_e32 v51, v51, v173
	v_fmac_f32_e32 v51, 0x3fb504f3, v238
	global_load_dword v238, v172, s[28:29] offset:64
	global_store_dword v172, v51, s[28:29] offset:0
	s_waitcnt vmcnt(31)
	v_sub_f32_e32 v177, v177, v132
	v_mul_f32_e32 v177, v177, v133
	v_fma_f32 v177, v240, v177, v244
	v_mul_f32_e32 v4, v4, v174
	v_fmac_f32_e32 v4, 0x3fb504f3, v177
	global_load_dword v177, v165, s[28:29] offset:-3968
	global_store_dword v165, v4, s[28:29] offset:-4032
	s_waitcnt vmcnt(31)
	v_sub_f32_e32 v178, v178, v134
	v_mul_f32_e32 v178, v178, v135
	v_fma_f32 v178, v240, v178, v244
	v_mul_f32_e32 v5, v5, v174
	v_fmac_f32_e32 v5, 0x3fb504f3, v178
	global_load_dword v178, v165, s[28:29] offset:128
	global_store_dword v165, v5, s[28:29] offset:64
	s_waitcnt vmcnt(31)
	v_sub_f32_e32 v179, v179, v136
	v_mul_f32_e32 v179, v179, v137
	v_fma_f32 v179, v240, v179, v244
	v_mul_f32_e32 v6, v6, v174
	v_fmac_f32_e32 v6, 0x3fb504f3, v179
	global_load_dword v179, v166, s[28:29] offset:-3968
	global_store_dword v166, v6, s[28:29] offset:-4032
	s_waitcnt vmcnt(31)
	v_sub_f32_e32 v224, v224, v138
	v_mul_f32_e32 v224, v224, v139
	v_fma_f32 v224, v240, v224, v244
	v_mul_f32_e32 v7, v7, v174
	v_fmac_f32_e32 v7, 0x3fb504f3, v224
	global_load_dword v224, v166, s[28:29] offset:128
	global_store_dword v166, v7, s[28:29] offset:64
	s_waitcnt vmcnt(31)
	v_sub_f32_e32 v225, v225, v140
	v_mul_f32_e32 v225, v225, v141
	v_fma_f32 v225, v240, v225, v244
	v_mul_f32_e32 v20, v20, v174
	v_fmac_f32_e32 v20, 0x3fb504f3, v225
	global_load_dword v225, v167, s[28:29] offset:-3968
	global_store_dword v167, v20, s[28:29] offset:-4032
	s_waitcnt vmcnt(31)
	v_sub_f32_e32 v226, v226, v142
	v_mul_f32_e32 v226, v226, v143
	v_fma_f32 v226, v240, v226, v244
	v_mul_f32_e32 v21, v21, v174
	v_fmac_f32_e32 v21, 0x3fb504f3, v226
	global_load_dword v226, v167, s[28:29] offset:128
	global_store_dword v167, v21, s[28:29] offset:64
	s_waitcnt vmcnt(31)
	v_sub_f32_e32 v227, v227, v144
	v_mul_f32_e32 v227, v227, v145
	v_fma_f32 v227, v240, v227, v244
	v_mul_f32_e32 v22, v22, v174
	v_fmac_f32_e32 v22, 0x3fb504f3, v227
	global_load_dword v227, v168, s[28:29] offset:-3968
	global_store_dword v168, v22, s[28:29] offset:-4032
	s_waitcnt vmcnt(31)
	v_sub_f32_e32 v228, v228, v146
	v_mul_f32_e32 v228, v228, v147
	v_fma_f32 v228, v240, v228, v244
	v_mul_f32_e32 v23, v23, v174
	v_fmac_f32_e32 v23, 0x3fb504f3, v228
	global_load_dword v228, v168, s[28:29] offset:128
	global_store_dword v168, v23, s[28:29] offset:64
	s_waitcnt vmcnt(31)
	v_sub_f32_e32 v229, v229, v148
	v_mul_f32_e32 v229, v229, v149
	v_fma_f32 v229, v240, v229, v244
	v_mul_f32_e32 v36, v36, v174
	v_fmac_f32_e32 v36, 0x3fb504f3, v229
	global_load_dword v229, v169, s[28:29] offset:-3968
	global_store_dword v169, v36, s[28:29] offset:-4032
	s_waitcnt vmcnt(31)
	v_sub_f32_e32 v230, v230, v150
	v_mul_f32_e32 v230, v230, v151
	v_fma_f32 v230, v240, v230, v244
	v_mul_f32_e32 v37, v37, v174
	v_fmac_f32_e32 v37, 0x3fb504f3, v230
	global_load_dword v230, v169, s[28:29] offset:128
	global_store_dword v169, v37, s[28:29] offset:64
	s_waitcnt vmcnt(31)
	v_sub_f32_e32 v231, v231, v152
	v_mul_f32_e32 v231, v231, v153
	v_fma_f32 v231, v240, v231, v244
	v_mul_f32_e32 v38, v38, v174
	v_fmac_f32_e32 v38, 0x3fb504f3, v231
	global_load_dword v231, v170, s[28:29] offset:-3968
	global_store_dword v170, v38, s[28:29] offset:-4032
	s_waitcnt vmcnt(31)
	v_sub_f32_e32 v234, v234, v154
	v_mul_f32_e32 v234, v234, v155
	v_fma_f32 v234, v240, v234, v244
	v_mul_f32_e32 v39, v39, v174
	v_fmac_f32_e32 v39, 0x3fb504f3, v234
	global_load_dword v234, v170, s[28:29] offset:128
	global_store_dword v170, v39, s[28:29] offset:64
	s_waitcnt vmcnt(31)
	v_sub_f32_e32 v235, v235, v156
	v_mul_f32_e32 v235, v235, v157
	v_fma_f32 v235, v240, v235, v244
	v_mul_f32_e32 v52, v52, v174
	v_fmac_f32_e32 v52, 0x3fb504f3, v235
	global_load_dword v235, v171, s[28:29] offset:-3968
	global_store_dword v171, v52, s[28:29] offset:-4032
	s_waitcnt vmcnt(31)
	v_sub_f32_e32 v236, v236, v158
	v_mul_f32_e32 v236, v236, v159
	v_fma_f32 v236, v240, v236, v244
	v_mul_f32_e32 v53, v53, v174
	v_fmac_f32_e32 v53, 0x3fb504f3, v236
	global_load_dword v236, v171, s[28:29] offset:128
	global_store_dword v171, v53, s[28:29] offset:64
	s_waitcnt vmcnt(31)
	v_sub_f32_e32 v237, v237, v160
	v_mul_f32_e32 v237, v237, v161
	v_fma_f32 v237, v240, v237, v244
	v_mul_f32_e32 v54, v54, v174
	v_fmac_f32_e32 v54, 0x3fb504f3, v237
	global_load_dword v237, v172, s[28:29] offset:-3968
	global_store_dword v172, v54, s[28:29] offset:-4032
	s_waitcnt vmcnt(31)
	v_sub_f32_e32 v238, v238, v162
	v_mul_f32_e32 v238, v238, v163
	v_fma_f32 v238, v240, v238, v244
	v_mul_f32_e32 v55, v55, v174
	v_fmac_f32_e32 v55, 0x3fb504f3, v238
	global_load_dword v238, v172, s[28:29] offset:128
	global_store_dword v172, v55, s[28:29] offset:64
	s_waitcnt vmcnt(31)
	v_sub_f32_e32 v177, v177, v132
	v_mul_f32_e32 v177, v177, v133
	v_fma_f32 v177, v241, v177, v245
	v_mul_f32_e32 v8, v8, v175
	v_fmac_f32_e32 v8, 0x3fb504f3, v177
	global_load_dword v177, v165, s[28:29] offset:-3904
	global_store_dword v165, v8, s[28:29] offset:-3968
	s_waitcnt vmcnt(31)
	v_sub_f32_e32 v178, v178, v134
	v_mul_f32_e32 v178, v178, v135
	v_fma_f32 v178, v241, v178, v245
	v_mul_f32_e32 v9, v9, v175
	v_fmac_f32_e32 v9, 0x3fb504f3, v178
	global_load_dword v178, v165, s[28:29] offset:192
	global_store_dword v165, v9, s[28:29] offset:128
	s_waitcnt vmcnt(31)
	v_sub_f32_e32 v179, v179, v136
	v_mul_f32_e32 v179, v179, v137
	v_fma_f32 v179, v241, v179, v245
	v_mul_f32_e32 v10, v10, v175
	v_fmac_f32_e32 v10, 0x3fb504f3, v179
	global_load_dword v179, v166, s[28:29] offset:-3904
	global_store_dword v166, v10, s[28:29] offset:-3968
	s_waitcnt vmcnt(31)
	v_sub_f32_e32 v224, v224, v138
	v_mul_f32_e32 v224, v224, v139
	v_fma_f32 v224, v241, v224, v245
	v_mul_f32_e32 v11, v11, v175
	v_fmac_f32_e32 v11, 0x3fb504f3, v224
	global_load_dword v224, v166, s[28:29] offset:192
	global_store_dword v166, v11, s[28:29] offset:128
	s_waitcnt vmcnt(31)
	v_sub_f32_e32 v225, v225, v140
	v_mul_f32_e32 v225, v225, v141
	v_fma_f32 v225, v241, v225, v245
	v_mul_f32_e32 v24, v24, v175
	v_fmac_f32_e32 v24, 0x3fb504f3, v225
	global_load_dword v225, v167, s[28:29] offset:-3904
	global_store_dword v167, v24, s[28:29] offset:-3968
	s_waitcnt vmcnt(31)
	v_sub_f32_e32 v226, v226, v142
	v_mul_f32_e32 v226, v226, v143
	v_fma_f32 v226, v241, v226, v245
	v_mul_f32_e32 v25, v25, v175
	v_fmac_f32_e32 v25, 0x3fb504f3, v226
	global_load_dword v226, v167, s[28:29] offset:192
	global_store_dword v167, v25, s[28:29] offset:128
	s_waitcnt vmcnt(31)
	v_sub_f32_e32 v227, v227, v144
	v_mul_f32_e32 v227, v227, v145
	v_fma_f32 v227, v241, v227, v245
	v_mul_f32_e32 v26, v26, v175
	v_fmac_f32_e32 v26, 0x3fb504f3, v227
	global_load_dword v227, v168, s[28:29] offset:-3904
	global_store_dword v168, v26, s[28:29] offset:-3968
	s_waitcnt vmcnt(31)
	v_sub_f32_e32 v228, v228, v146
	v_mul_f32_e32 v228, v228, v147
	v_fma_f32 v228, v241, v228, v245
	v_mul_f32_e32 v27, v27, v175
	v_fmac_f32_e32 v27, 0x3fb504f3, v228
	global_load_dword v228, v168, s[28:29] offset:192
	global_store_dword v168, v27, s[28:29] offset:128
	s_waitcnt vmcnt(31)
	v_sub_f32_e32 v229, v229, v148
	v_mul_f32_e32 v229, v229, v149
	v_fma_f32 v229, v241, v229, v245
	v_mul_f32_e32 v40, v40, v175
	v_fmac_f32_e32 v40, 0x3fb504f3, v229
	global_load_dword v229, v169, s[28:29] offset:-3904
	global_store_dword v169, v40, s[28:29] offset:-3968
	s_waitcnt vmcnt(31)
	v_sub_f32_e32 v230, v230, v150
	v_mul_f32_e32 v230, v230, v151
	v_fma_f32 v230, v241, v230, v245
	v_mul_f32_e32 v41, v41, v175
	v_fmac_f32_e32 v41, 0x3fb504f3, v230
	global_load_dword v230, v169, s[28:29] offset:192
	global_store_dword v169, v41, s[28:29] offset:128
	s_waitcnt vmcnt(31)
	v_sub_f32_e32 v231, v231, v152
	v_mul_f32_e32 v231, v231, v153
	v_fma_f32 v231, v241, v231, v245
	v_mul_f32_e32 v42, v42, v175
	v_fmac_f32_e32 v42, 0x3fb504f3, v231
	global_load_dword v231, v170, s[28:29] offset:-3904
	global_store_dword v170, v42, s[28:29] offset:-3968
	s_waitcnt vmcnt(31)
	v_sub_f32_e32 v234, v234, v154
	v_mul_f32_e32 v234, v234, v155
	v_fma_f32 v234, v241, v234, v245
	v_mul_f32_e32 v43, v43, v175
	v_fmac_f32_e32 v43, 0x3fb504f3, v234
	global_load_dword v234, v170, s[28:29] offset:192
	global_store_dword v170, v43, s[28:29] offset:128
	s_waitcnt vmcnt(31)
	v_sub_f32_e32 v235, v235, v156
	v_mul_f32_e32 v235, v235, v157
	v_fma_f32 v235, v241, v235, v245
	v_mul_f32_e32 v56, v56, v175
	v_fmac_f32_e32 v56, 0x3fb504f3, v235
	global_load_dword v235, v171, s[28:29] offset:-3904
	global_store_dword v171, v56, s[28:29] offset:-3968
	s_waitcnt vmcnt(31)
	v_sub_f32_e32 v236, v236, v158
	v_mul_f32_e32 v236, v236, v159
	v_fma_f32 v236, v241, v236, v245
	v_mul_f32_e32 v57, v57, v175
	v_fmac_f32_e32 v57, 0x3fb504f3, v236
	global_load_dword v236, v171, s[28:29] offset:192
	global_store_dword v171, v57, s[28:29] offset:128
	s_waitcnt vmcnt(31)
	v_sub_f32_e32 v237, v237, v160
	v_mul_f32_e32 v237, v237, v161
	v_fma_f32 v237, v241, v237, v245
	v_mul_f32_e32 v58, v58, v175
	v_fmac_f32_e32 v58, 0x3fb504f3, v237
	global_load_dword v237, v172, s[28:29] offset:-3904
	global_store_dword v172, v58, s[28:29] offset:-3968
	s_waitcnt vmcnt(31)
	v_sub_f32_e32 v238, v238, v162
	v_mul_f32_e32 v238, v238, v163
	v_fma_f32 v238, v241, v238, v245
	v_mul_f32_e32 v59, v59, v175
	v_fmac_f32_e32 v59, 0x3fb504f3, v238
	global_load_dword v238, v172, s[28:29] offset:192
	global_store_dword v172, v59, s[28:29] offset:128
	s_waitcnt vmcnt(31)
	v_sub_f32_e32 v177, v177, v132
	v_mul_f32_e32 v177, v177, v133
	v_fma_f32 v177, v242, v177, v112
	v_mul_f32_e32 v12, v12, v176
	v_fmac_f32_e32 v12, 0x3fb504f3, v177
	global_store_dword v165, v12, s[28:29] offset:-3904
	s_waitcnt vmcnt(30)
	v_sub_f32_e32 v178, v178, v134
	v_mul_f32_e32 v178, v178, v135
	v_fma_f32 v178, v242, v178, v112
	v_mul_f32_e32 v13, v13, v176
	v_fmac_f32_e32 v13, 0x3fb504f3, v178
	global_store_dword v165, v13, s[28:29] offset:192
	s_waitcnt vmcnt(29)
	v_sub_f32_e32 v179, v179, v136
	v_mul_f32_e32 v179, v179, v137
	v_fma_f32 v179, v242, v179, v112
	v_mul_f32_e32 v14, v14, v176
	v_fmac_f32_e32 v14, 0x3fb504f3, v179
	global_store_dword v166, v14, s[28:29] offset:-3904
	s_waitcnt vmcnt(28)
	v_sub_f32_e32 v224, v224, v138
	v_mul_f32_e32 v224, v224, v139
	v_fma_f32 v224, v242, v224, v112
	v_mul_f32_e32 v15, v15, v176
	v_fmac_f32_e32 v15, 0x3fb504f3, v224
	global_store_dword v166, v15, s[28:29] offset:192
	s_waitcnt vmcnt(27)
	v_sub_f32_e32 v225, v225, v140
	v_mul_f32_e32 v225, v225, v141
	v_fma_f32 v225, v242, v225, v112
	v_mul_f32_e32 v28, v28, v176
	v_fmac_f32_e32 v28, 0x3fb504f3, v225
	global_store_dword v167, v28, s[28:29] offset:-3904
	s_waitcnt vmcnt(26)
	v_sub_f32_e32 v226, v226, v142
	v_mul_f32_e32 v226, v226, v143
	v_fma_f32 v226, v242, v226, v112
	v_mul_f32_e32 v29, v29, v176
	v_fmac_f32_e32 v29, 0x3fb504f3, v226
	global_store_dword v167, v29, s[28:29] offset:192
	s_waitcnt vmcnt(25)
	v_sub_f32_e32 v227, v227, v144
	v_mul_f32_e32 v227, v227, v145
	v_fma_f32 v227, v242, v227, v112
	v_mul_f32_e32 v30, v30, v176
	v_fmac_f32_e32 v30, 0x3fb504f3, v227
	global_store_dword v168, v30, s[28:29] offset:-3904
	s_waitcnt vmcnt(24)
	v_sub_f32_e32 v228, v228, v146
	v_mul_f32_e32 v228, v228, v147
	v_fma_f32 v228, v242, v228, v112
	v_mul_f32_e32 v31, v31, v176
	v_fmac_f32_e32 v31, 0x3fb504f3, v228
	global_store_dword v168, v31, s[28:29] offset:192
	s_waitcnt vmcnt(23)
	v_sub_f32_e32 v229, v229, v148
	v_mul_f32_e32 v229, v229, v149
	v_fma_f32 v229, v242, v229, v112
	v_mul_f32_e32 v44, v44, v176
	v_fmac_f32_e32 v44, 0x3fb504f3, v229
	global_store_dword v169, v44, s[28:29] offset:-3904
	s_waitcnt vmcnt(22)
	v_sub_f32_e32 v230, v230, v150
	v_mul_f32_e32 v230, v230, v151
	v_fma_f32 v230, v242, v230, v112
	v_mul_f32_e32 v45, v45, v176
	v_fmac_f32_e32 v45, 0x3fb504f3, v230
	global_store_dword v169, v45, s[28:29] offset:192
	s_waitcnt vmcnt(21)
	v_sub_f32_e32 v231, v231, v152
	v_mul_f32_e32 v231, v231, v153
	v_fma_f32 v231, v242, v231, v112
	v_mul_f32_e32 v46, v46, v176
	v_fmac_f32_e32 v46, 0x3fb504f3, v231
	global_store_dword v170, v46, s[28:29] offset:-3904
	s_waitcnt vmcnt(20)
	v_sub_f32_e32 v234, v234, v154
	v_mul_f32_e32 v234, v234, v155
	v_fma_f32 v234, v242, v234, v112
	v_mul_f32_e32 v47, v47, v176
	v_fmac_f32_e32 v47, 0x3fb504f3, v234
	global_store_dword v170, v47, s[28:29] offset:192
	s_waitcnt vmcnt(19)
	v_sub_f32_e32 v235, v235, v156
	v_mul_f32_e32 v235, v235, v157
	v_fma_f32 v235, v242, v235, v112
	v_mul_f32_e32 v60, v60, v176
	v_fmac_f32_e32 v60, 0x3fb504f3, v235
	global_store_dword v171, v60, s[28:29] offset:-3904
	s_waitcnt vmcnt(18)
	v_sub_f32_e32 v236, v236, v158
	v_mul_f32_e32 v236, v236, v159
	v_fma_f32 v236, v242, v236, v112
	v_mul_f32_e32 v61, v61, v176
	v_fmac_f32_e32 v61, 0x3fb504f3, v236
	global_store_dword v171, v61, s[28:29] offset:192
	s_waitcnt vmcnt(17)
	v_sub_f32_e32 v237, v237, v160
	v_mul_f32_e32 v237, v237, v161
	v_fma_f32 v237, v242, v237, v112
	v_mul_f32_e32 v62, v62, v176
	v_fmac_f32_e32 v62, 0x3fb504f3, v237
	global_store_dword v172, v62, s[28:29] offset:-3904
	s_waitcnt vmcnt(16)
	v_sub_f32_e32 v238, v238, v162
	v_mul_f32_e32 v238, v238, v163
	v_fma_f32 v238, v242, v238, v112
	v_mul_f32_e32 v63, v63, v176
	v_fmac_f32_e32 v63, 0x3fb504f3, v238
	global_store_dword v172, v63, s[28:29] offset:192
	v_add_u32_e32 v180, 64, v180
	v_lshl_add_u32 v164, v180, 12, v181
	v_add_u32_e32 v165, 0x1000, v164
	v_add_u32_e32 v166, 0x3000, v164
	v_add_u32_e32 v167, 0x11000, v164
	v_add_u32_e32 v168, 0x13000, v164
	v_add_u32_e32 v169, 0x21000, v164
	v_add_u32_e32 v170, 0x23000, v164
	v_add_u32_e32 v171, 0x31000, v164
	v_add_u32_e32 v172, 0x33000, v164
	v_lshlrev_b32_e32 v35, 3, v180
	v_add_u32_e32 v35, 0x1e200000, v35
	v_mov_b32_e32 v49, s71
	v_mul_u32_u24_e32 v49, 3, v49
	v_add_u32_e32 v49, 1, v49
	v_lshl_add_u32 v48, v49, 12, v181
	global_load_dwordx2 v[132:133], v35, s[30:31] offset:0
	global_load_dwordx2 v[134:135], v35, s[30:31] offset:8
	global_load_dwordx2 v[136:137], v35, s[30:31] offset:16
	global_load_dwordx2 v[138:139], v35, s[30:31] offset:24
	global_load_dwordx2 v[140:141], v35, s[30:31] offset:128
	global_load_dwordx2 v[142:143], v35, s[30:31] offset:136
	global_load_dwordx2 v[144:145], v35, s[30:31] offset:144
	global_load_dwordx2 v[146:147], v35, s[30:31] offset:152
	global_load_dwordx2 v[148:149], v35, s[30:31] offset:256
	global_load_dwordx2 v[150:151], v35, s[30:31] offset:264
	global_load_dwordx2 v[152:153], v35, s[30:31] offset:272
	global_load_dwordx2 v[154:155], v35, s[30:31] offset:280
	global_load_dwordx2 v[156:157], v35, s[30:31] offset:384
	global_load_dwordx2 v[158:159], v35, s[30:31] offset:392
	global_load_dwordx2 v[160:161], v35, s[30:31] offset:400
	global_load_dwordx2 v[162:163], v35, s[30:31] offset:408
	global_load_dword v3, v48, s[24:25] offset:0
	global_load_dword v19, v48, s[26:27] offset:0
	global_load_dword v16, v48, s[24:25] offset:64
	global_load_dword v32, v48, s[26:27] offset:64
	global_load_dword v17, v48, s[24:25] offset:128
	global_load_dword v33, v48, s[26:27] offset:128
	global_load_dword v18, v48, s[24:25] offset:192
	global_load_dword v34, v48, s[26:27] offset:192
	global_load_dword v173, v[246:247], off offset:0
	global_load_dword v174, v[246:247], off offset:64
	global_load_dword v175, v[246:247], off offset:128
	global_load_dword v176, v[246:247], off offset:192
	global_load_dword v177, v165, s[28:29] offset:-4096
	global_load_dword v178, v165, s[28:29] offset:0
	global_load_dword v179, v166, s[28:29] offset:-4096
	global_load_dword v224, v166, s[28:29] offset:0
	global_load_dword v225, v167, s[28:29] offset:-4096
	global_load_dword v226, v167, s[28:29] offset:0
	global_load_dword v227, v168, s[28:29] offset:-4096
	global_load_dword v228, v168, s[28:29] offset:0
	global_load_dword v229, v169, s[28:29] offset:-4096
	global_load_dword v230, v169, s[28:29] offset:0
	global_load_dword v231, v170, s[28:29] offset:-4096
	global_load_dword v234, v170, s[28:29] offset:0
	global_load_dword v235, v171, s[28:29] offset:-4096
	global_load_dword v236, v171, s[28:29] offset:0
	global_load_dword v237, v172, s[28:29] offset:-4096
	global_load_dword v238, v172, s[28:29] offset:0
	global_load_dword v239, v165, s[28:29] offset:-4032
	global_load_dword v240, v165, s[28:29] offset:64
	global_load_dword v241, v166, s[28:29] offset:-4032
	global_load_dword v242, v166, s[28:29] offset:64
	global_load_dword v243, v167, s[28:29] offset:-4032
	global_load_dword v244, v167, s[28:29] offset:64
	global_load_dword v245, v168, s[28:29] offset:-4032
	global_load_dword v112, v168, s[28:29] offset:64
	global_load_dword v115, v169, s[28:29] offset:-4032
	global_load_dword v208, v169, s[28:29] offset:64
	global_load_dword v223, v170, s[28:29] offset:-4032
	global_load_dword v233, v170, s[28:29] offset:64
	global_load_dword v248, v171, s[28:29] offset:-4032
	global_load_dword v0, v171, s[28:29] offset:64
	global_load_dword v1, v172, s[28:29] offset:-4032
	global_load_dword v2, v172, s[28:29] offset:64
	s_waitcnt vmcnt(31)
	v_add_f32_e32 v173, 1.0, v173
	v_add_f32_e32 v174, 1.0, v174
	v_add_f32_e32 v175, 1.0, v175
	v_add_f32_e32 v176, 1.0, v176
	v_mul_f32_e32 v173, 0.5, v173
	v_mul_f32_e32 v174, 0.5, v174
	v_mul_f32_e32 v175, 0.5, v175
	v_mul_f32_e32 v176, 0.5, v176
	v_sub_f32_e32 v177, v177, v132
	v_mul_f32_e32 v177, v177, v133
	v_fma_f32 v177, v3, v177, v19
	v_mul_f32_e32 v64, v64, v173
	v_fmac_f32_e32 v64, 0x3fb504f3, v177
	global_load_dword v177, v165, s[28:29] offset:-3968
	global_store_dword v165, v64, s[28:29] offset:-4096
	s_waitcnt vmcnt(32)
	v_sub_f32_e32 v178, v178, v134
	v_mul_f32_e32 v178, v178, v135
	v_fma_f32 v178, v3, v178, v19
	v_mul_f32_e32 v65, v65, v173
	v_fmac_f32_e32 v65, 0x3fb504f3, v178
	global_load_dword v178, v165, s[28:29] offset:128
	global_store_dword v165, v65, s[28:29] offset:0
	s_waitcnt vmcnt(33)
	v_sub_f32_e32 v179, v179, v136
	v_mul_f32_e32 v179, v179, v137
	v_fma_f32 v179, v3, v179, v19
	v_mul_f32_e32 v66, v66, v173
	v_fmac_f32_e32 v66, 0x3fb504f3, v179
	global_load_dword v179, v166, s[28:29] offset:-3968
	global_store_dword v166, v66, s[28:29] offset:-4096
	s_waitcnt vmcnt(34)
	v_sub_f32_e32 v224, v224, v138
	v_mul_f32_e32 v224, v224, v139
	v_fma_f32 v224, v3, v224, v19
	v_mul_f32_e32 v67, v67, v173
	v_fmac_f32_e32 v67, 0x3fb504f3, v224
	global_load_dword v224, v166, s[28:29] offset:128
	global_store_dword v166, v67, s[28:29] offset:0
	s_waitcnt vmcnt(35)
	v_sub_f32_e32 v225, v225, v140
	v_mul_f32_e32 v225, v225, v141
	v_fma_f32 v225, v3, v225, v19
	v_mul_f32_e32 v80, v80, v173
	v_fmac_f32_e32 v80, 0x3fb504f3, v225
	global_load_dword v225, v167, s[28:29] offset:-3968
	global_store_dword v167, v80, s[28:29] offset:-4096
	s_waitcnt vmcnt(36)
	v_sub_f32_e32 v226, v226, v142
	v_mul_f32_e32 v226, v226, v143
	v_fma_f32 v226, v3, v226, v19
	v_mul_f32_e32 v81, v81, v173
	v_fmac_f32_e32 v81, 0x3fb504f3, v226
	global_load_dword v226, v167, s[28:29] offset:128
	global_store_dword v167, v81, s[28:29] offset:0
	s_waitcnt vmcnt(37)
	v_sub_f32_e32 v227, v227, v144
	v_mul_f32_e32 v227, v227, v145
	v_fma_f32 v227, v3, v227, v19
	v_mul_f32_e32 v82, v82, v173
	v_fmac_f32_e32 v82, 0x3fb504f3, v227
	global_load_dword v227, v168, s[28:29] offset:-3968
	global_store_dword v168, v82, s[28:29] offset:-4096
	s_waitcnt vmcnt(38)
	v_sub_f32_e32 v228, v228, v146
	v_mul_f32_e32 v228, v228, v147
	v_fma_f32 v228, v3, v228, v19
	v_mul_f32_e32 v83, v83, v173
	v_fmac_f32_e32 v83, 0x3fb504f3, v228
	global_load_dword v228, v168, s[28:29] offset:128
	global_store_dword v168, v83, s[28:29] offset:0
	s_waitcnt vmcnt(39)
	v_sub_f32_e32 v229, v229, v148
	v_mul_f32_e32 v229, v229, v149
	v_fma_f32 v229, v3, v229, v19
	v_mul_f32_e32 v96, v96, v173
	v_fmac_f32_e32 v96, 0x3fb504f3, v229
	global_load_dword v229, v169, s[28:29] offset:-3968
	global_store_dword v169, v96, s[28:29] offset:-4096
	s_waitcnt vmcnt(40)
	v_sub_f32_e32 v230, v230, v150
	v_mul_f32_e32 v230, v230, v151
	v_fma_f32 v230, v3, v230, v19
	v_mul_f32_e32 v97, v97, v173
	v_fmac_f32_e32 v97, 0x3fb504f3, v230
	global_load_dword v230, v169, s[28:29] offset:128
	global_store_dword v169, v97, s[28:29] offset:0
	s_waitcnt vmcnt(41)
	v_sub_f32_e32 v231, v231, v152
	v_mul_f32_e32 v231, v231, v153
	v_fma_f32 v231, v3, v231, v19
	v_mul_f32_e32 v98, v98, v173
	v_fmac_f32_e32 v98, 0x3fb504f3, v231
	global_load_dword v231, v170, s[28:29] offset:-3968
	global_store_dword v170, v98, s[28:29] offset:-4096
	s_waitcnt vmcnt(42)
	v_sub_f32_e32 v234, v234, v154
	v_mul_f32_e32 v234, v234, v155
	v_fma_f32 v234, v3, v234, v19
	v_mul_f32_e32 v99, v99, v173
	v_fmac_f32_e32 v99, 0x3fb504f3, v234
	global_load_dword v234, v170, s[28:29] offset:128
	global_store_dword v170, v99, s[28:29] offset:0
	s_waitcnt vmcnt(43)
	v_sub_f32_e32 v235, v235, v156
	v_mul_f32_e32 v235, v235, v157
	v_fma_f32 v235, v3, v235, v19
	v_mul_f32_e32 v116, v116, v173
	v_fmac_f32_e32 v116, 0x3fb504f3, v235
	global_load_dword v235, v171, s[28:29] offset:-3968
	global_store_dword v171, v116, s[28:29] offset:-4096
	s_waitcnt vmcnt(44)
	v_sub_f32_e32 v236, v236, v158
	v_mul_f32_e32 v236, v236, v159
	v_fma_f32 v236, v3, v236, v19
	v_mul_f32_e32 v117, v117, v173
	v_fmac_f32_e32 v117, 0x3fb504f3, v236
	global_load_dword v236, v171, s[28:29] offset:128
	global_store_dword v171, v117, s[28:29] offset:0
	s_waitcnt vmcnt(45)
	v_sub_f32_e32 v237, v237, v160
	v_mul_f32_e32 v237, v237, v161
	v_fma_f32 v237, v3, v237, v19
	v_mul_f32_e32 v118, v118, v173
	v_fmac_f32_e32 v118, 0x3fb504f3, v237
	global_load_dword v237, v172, s[28:29] offset:-3968
	global_store_dword v172, v118, s[28:29] offset:-4096
	s_waitcnt vmcnt(46)
	v_sub_f32_e32 v238, v238, v162
	v_mul_f32_e32 v238, v238, v163
	v_fma_f32 v238, v3, v238, v19
	v_mul_f32_e32 v119, v119, v173
	v_fmac_f32_e32 v119, 0x3fb504f3, v238
	global_load_dword v238, v172, s[28:29] offset:128
	global_store_dword v172, v119, s[28:29] offset:0
	s_waitcnt vmcnt(47)
	v_sub_f32_e32 v239, v239, v132
	v_mul_f32_e32 v239, v239, v133
	v_fma_f32 v239, v16, v239, v32
	v_mul_f32_e32 v68, v68, v174
	v_fmac_f32_e32 v68, 0x3fb504f3, v239
	global_load_dword v239, v165, s[28:29] offset:-3904
	global_store_dword v165, v68, s[28:29] offset:-4032
	s_waitcnt vmcnt(48)
	v_sub_f32_e32 v240, v240, v134
	v_mul_f32_e32 v240, v240, v135
	v_fma_f32 v240, v16, v240, v32
	v_mul_f32_e32 v69, v69, v174
	v_fmac_f32_e32 v69, 0x3fb504f3, v240
	global_load_dword v240, v165, s[28:29] offset:192
	global_store_dword v165, v69, s[28:29] offset:64
	s_waitcnt vmcnt(49)
	v_sub_f32_e32 v241, v241, v136
	v_mul_f32_e32 v241, v241, v137
	v_fma_f32 v241, v16, v241, v32
	v_mul_f32_e32 v70, v70, v174
	v_fmac_f32_e32 v70, 0x3fb504f3, v241
	global_load_dword v241, v166, s[28:29] offset:-3904
	global_store_dword v166, v70, s[28:29] offset:-4032
	s_waitcnt vmcnt(50)
	v_sub_f32_e32 v242, v242, v138
	v_mul_f32_e32 v242, v242, v139
	v_fma_f32 v242, v16, v242, v32
	v_mul_f32_e32 v71, v71, v174
	v_fmac_f32_e32 v71, 0x3fb504f3, v242
	global_load_dword v242, v166, s[28:29] offset:192
	global_store_dword v166, v71, s[28:29] offset:64
	s_waitcnt vmcnt(51)
	v_sub_f32_e32 v243, v243, v140
	v_mul_f32_e32 v243, v243, v141
	v_fma_f32 v243, v16, v243, v32
	v_mul_f32_e32 v84, v84, v174
	v_fmac_f32_e32 v84, 0x3fb504f3, v243
	global_load_dword v243, v167, s[28:29] offset:-3904
	global_store_dword v167, v84, s[28:29] offset:-4032
	s_waitcnt vmcnt(52)
	v_sub_f32_e32 v244, v244, v142
	v_mul_f32_e32 v244, v244, v143
	v_fma_f32 v244, v16, v244, v32
	v_mul_f32_e32 v85, v85, v174
	v_fmac_f32_e32 v85, 0x3fb504f3, v244
	global_load_dword v244, v167, s[28:29] offset:192
	global_store_dword v167, v85, s[28:29] offset:64
	s_waitcnt vmcnt(53)
	v_sub_f32_e32 v245, v245, v144
	v_mul_f32_e32 v245, v245, v145
	v_fma_f32 v245, v16, v245, v32
	v_mul_f32_e32 v86, v86, v174
	v_fmac_f32_e32 v86, 0x3fb504f3, v245
	global_load_dword v245, v168, s[28:29] offset:-3904
	global_store_dword v168, v86, s[28:29] offset:-4032
	s_waitcnt vmcnt(54)
	v_sub_f32_e32 v112, v112, v146
	v_mul_f32_e32 v112, v112, v147
	v_fma_f32 v112, v16, v112, v32
	v_mul_f32_e32 v87, v87, v174
	v_fmac_f32_e32 v87, 0x3fb504f3, v112
	global_load_dword v112, v168, s[28:29] offset:192
	global_store_dword v168, v87, s[28:29] offset:64
	s_waitcnt vmcnt(55)
	v_sub_f32_e32 v115, v115, v148
	v_mul_f32_e32 v115, v115, v149
	v_fma_f32 v115, v16, v115, v32
	v_mul_f32_e32 v100, v100, v174
	v_fmac_f32_e32 v100, 0x3fb504f3, v115
	global_load_dword v115, v169, s[28:29] offset:-3904
	global_store_dword v169, v100, s[28:29] offset:-4032
	s_waitcnt vmcnt(56)
	v_sub_f32_e32 v208, v208, v150
	v_mul_f32_e32 v208, v208, v151
	v_fma_f32 v208, v16, v208, v32
	v_mul_f32_e32 v101, v101, v174
	v_fmac_f32_e32 v101, 0x3fb504f3, v208
	global_load_dword v208, v169, s[28:29] offset:192
	global_store_dword v169, v101, s[28:29] offset:64
	s_waitcnt vmcnt(57)
	v_sub_f32_e32 v223, v223, v152
	v_mul_f32_e32 v223, v223, v153
	v_fma_f32 v223, v16, v223, v32
	v_mul_f32_e32 v102, v102, v174
	v_fmac_f32_e32 v102, 0x3fb504f3, v223
	global_load_dword v223, v170, s[28:29] offset:-3904
	global_store_dword v170, v102, s[28:29] offset:-4032
	s_waitcnt vmcnt(58)
	v_sub_f32_e32 v233, v233, v154
	v_mul_f32_e32 v233, v233, v155
	v_fma_f32 v233, v16, v233, v32
	v_mul_f32_e32 v103, v103, v174
	v_fmac_f32_e32 v103, 0x3fb504f3, v233
	global_load_dword v233, v170, s[28:29] offset:192
	global_store_dword v170, v103, s[28:29] offset:64
	s_waitcnt vmcnt(59)
	v_sub_f32_e32 v248, v248, v156
	v_mul_f32_e32 v248, v248, v157
	v_fma_f32 v248, v16, v248, v32
	v_mul_f32_e32 v120, v120, v174
	v_fmac_f32_e32 v120, 0x3fb504f3, v248
	global_load_dword v248, v171, s[28:29] offset:-3904
	global_store_dword v171, v120, s[28:29] offset:-4032
	s_waitcnt vmcnt(60)
	v_sub_f32_e32 v0, v0, v158
	v_mul_f32_e32 v0, v0, v159
	v_fma_f32 v0, v16, v0, v32
	v_mul_f32_e32 v121, v121, v174
	v_fmac_f32_e32 v121, 0x3fb504f3, v0
	global_load_dword v0, v171, s[28:29] offset:192
	global_store_dword v171, v121, s[28:29] offset:64
	s_waitcnt vmcnt(61)
	v_sub_f32_e32 v1, v1, v160
	v_mul_f32_e32 v1, v1, v161
	v_fma_f32 v1, v16, v1, v32
	v_mul_f32_e32 v122, v122, v174
	v_fmac_f32_e32 v122, 0x3fb504f3, v1
	global_load_dword v1, v172, s[28:29] offset:-3904
	global_store_dword v172, v122, s[28:29] offset:-4032
	s_waitcnt vmcnt(62)
	v_sub_f32_e32 v2, v2, v162
	v_mul_f32_e32 v2, v2, v163
	v_fma_f32 v2, v16, v2, v32
	v_mul_f32_e32 v123, v123, v174
	v_fmac_f32_e32 v123, 0x3fb504f3, v2
	global_load_dword v2, v172, s[28:29] offset:192
	global_store_dword v172, v123, s[28:29] offset:64
	s_waitcnt vmcnt(63)
	v_sub_f32_e32 v177, v177, v132
	v_mul_f32_e32 v177, v177, v133
	v_fma_f32 v177, v17, v177, v33
	v_mul_f32_e32 v72, v72, v175
	v_fmac_f32_e32 v72, 0x3fb504f3, v177
	global_store_dword v165, v72, s[28:29] offset:-3968
	s_waitcnt vmcnt(62)
	v_sub_f32_e32 v178, v178, v134
	v_mul_f32_e32 v178, v178, v135
	v_fma_f32 v178, v17, v178, v33
	v_mul_f32_e32 v73, v73, v175
	v_fmac_f32_e32 v73, 0x3fb504f3, v178
	global_store_dword v165, v73, s[28:29] offset:128
	s_waitcnt vmcnt(61)
	v_sub_f32_e32 v179, v179, v136
	v_mul_f32_e32 v179, v179, v137
	v_fma_f32 v179, v17, v179, v33
	v_mul_f32_e32 v74, v74, v175
	v_fmac_f32_e32 v74, 0x3fb504f3, v179
	global_store_dword v166, v74, s[28:29] offset:-3968
	s_waitcnt vmcnt(60)
	v_sub_f32_e32 v224, v224, v138
	v_mul_f32_e32 v224, v224, v139
	v_fma_f32 v224, v17, v224, v33
	v_mul_f32_e32 v75, v75, v175
	v_fmac_f32_e32 v75, 0x3fb504f3, v224
	global_store_dword v166, v75, s[28:29] offset:128
	s_waitcnt vmcnt(59)
	v_sub_f32_e32 v225, v225, v140
	v_mul_f32_e32 v225, v225, v141
	v_fma_f32 v225, v17, v225, v33
	v_mul_f32_e32 v88, v88, v175
	v_fmac_f32_e32 v88, 0x3fb504f3, v225
	global_store_dword v167, v88, s[28:29] offset:-3968
	s_waitcnt vmcnt(58)
	v_sub_f32_e32 v226, v226, v142
	v_mul_f32_e32 v226, v226, v143
	v_fma_f32 v226, v17, v226, v33
	v_mul_f32_e32 v89, v89, v175
	v_fmac_f32_e32 v89, 0x3fb504f3, v226
	global_store_dword v167, v89, s[28:29] offset:128
	s_waitcnt vmcnt(57)
	v_sub_f32_e32 v227, v227, v144
	v_mul_f32_e32 v227, v227, v145
	v_fma_f32 v227, v17, v227, v33
	v_mul_f32_e32 v90, v90, v175
	v_fmac_f32_e32 v90, 0x3fb504f3, v227
	global_store_dword v168, v90, s[28:29] offset:-3968
	s_waitcnt vmcnt(56)
	v_sub_f32_e32 v228, v228, v146
	v_mul_f32_e32 v228, v228, v147
	v_fma_f32 v228, v17, v228, v33
	v_mul_f32_e32 v91, v91, v175
	v_fmac_f32_e32 v91, 0x3fb504f3, v228
	global_store_dword v168, v91, s[28:29] offset:128
	s_waitcnt vmcnt(55)
	v_sub_f32_e32 v229, v229, v148
	v_mul_f32_e32 v229, v229, v149
	v_fma_f32 v229, v17, v229, v33
	v_mul_f32_e32 v104, v104, v175
	v_fmac_f32_e32 v104, 0x3fb504f3, v229
	global_store_dword v169, v104, s[28:29] offset:-3968
	s_waitcnt vmcnt(54)
	v_sub_f32_e32 v230, v230, v150
	v_mul_f32_e32 v230, v230, v151
	v_fma_f32 v230, v17, v230, v33
	v_mul_f32_e32 v105, v105, v175
	v_fmac_f32_e32 v105, 0x3fb504f3, v230
	global_store_dword v169, v105, s[28:29] offset:128
	s_waitcnt vmcnt(53)
	v_sub_f32_e32 v231, v231, v152
	v_mul_f32_e32 v231, v231, v153
	v_fma_f32 v231, v17, v231, v33
	v_mul_f32_e32 v106, v106, v175
	v_fmac_f32_e32 v106, 0x3fb504f3, v231
	global_store_dword v170, v106, s[28:29] offset:-3968
	s_waitcnt vmcnt(52)
	v_sub_f32_e32 v234, v234, v154
	v_mul_f32_e32 v234, v234, v155
	v_fma_f32 v234, v17, v234, v33
	v_mul_f32_e32 v107, v107, v175
	v_fmac_f32_e32 v107, 0x3fb504f3, v234
	global_store_dword v170, v107, s[28:29] offset:128
	s_waitcnt vmcnt(51)
	v_sub_f32_e32 v235, v235, v156
	v_mul_f32_e32 v235, v235, v157
	v_fma_f32 v235, v17, v235, v33
	v_mul_f32_e32 v124, v124, v175
	v_fmac_f32_e32 v124, 0x3fb504f3, v235
	global_store_dword v171, v124, s[28:29] offset:-3968
	s_waitcnt vmcnt(50)
	v_sub_f32_e32 v236, v236, v158
	v_mul_f32_e32 v236, v236, v159
	v_fma_f32 v236, v17, v236, v33
	v_mul_f32_e32 v125, v125, v175
	v_fmac_f32_e32 v125, 0x3fb504f3, v236
	global_store_dword v171, v125, s[28:29] offset:128
	s_waitcnt vmcnt(49)
	v_sub_f32_e32 v237, v237, v160
	v_mul_f32_e32 v237, v237, v161
	v_fma_f32 v237, v17, v237, v33
	v_mul_f32_e32 v126, v126, v175
	v_fmac_f32_e32 v126, 0x3fb504f3, v237
	global_store_dword v172, v126, s[28:29] offset:-3968
	s_waitcnt vmcnt(48)
	v_sub_f32_e32 v238, v238, v162
	v_mul_f32_e32 v238, v238, v163
	v_fma_f32 v238, v17, v238, v33
	v_mul_f32_e32 v127, v127, v175
	v_fmac_f32_e32 v127, 0x3fb504f3, v238
	global_store_dword v172, v127, s[28:29] offset:128
	s_waitcnt vmcnt(47)
	v_sub_f32_e32 v239, v239, v132
	v_mul_f32_e32 v239, v239, v133
	v_fma_f32 v239, v18, v239, v34
	v_mul_f32_e32 v76, v76, v176
	v_fmac_f32_e32 v76, 0x3fb504f3, v239
	global_store_dword v165, v76, s[28:29] offset:-3904
	s_waitcnt vmcnt(46)
	v_sub_f32_e32 v240, v240, v134
	v_mul_f32_e32 v240, v240, v135
	v_fma_f32 v240, v18, v240, v34
	v_mul_f32_e32 v77, v77, v176
	v_fmac_f32_e32 v77, 0x3fb504f3, v240
	global_store_dword v165, v77, s[28:29] offset:192
	s_waitcnt vmcnt(45)
	v_sub_f32_e32 v241, v241, v136
	v_mul_f32_e32 v241, v241, v137
	v_fma_f32 v241, v18, v241, v34
	v_mul_f32_e32 v78, v78, v176
	v_fmac_f32_e32 v78, 0x3fb504f3, v241
	global_store_dword v166, v78, s[28:29] offset:-3904
	s_waitcnt vmcnt(44)
	v_sub_f32_e32 v242, v242, v138
	v_mul_f32_e32 v242, v242, v139
	v_fma_f32 v242, v18, v242, v34
	v_mul_f32_e32 v79, v79, v176
	v_fmac_f32_e32 v79, 0x3fb504f3, v242
	global_store_dword v166, v79, s[28:29] offset:192
	s_waitcnt vmcnt(43)
	v_sub_f32_e32 v243, v243, v140
	v_mul_f32_e32 v243, v243, v141
	v_fma_f32 v243, v18, v243, v34
	v_mul_f32_e32 v92, v92, v176
	v_fmac_f32_e32 v92, 0x3fb504f3, v243
	global_store_dword v167, v92, s[28:29] offset:-3904
	s_waitcnt vmcnt(42)
	v_sub_f32_e32 v244, v244, v142
	v_mul_f32_e32 v244, v244, v143
	v_fma_f32 v244, v18, v244, v34
	v_mul_f32_e32 v93, v93, v176
	v_fmac_f32_e32 v93, 0x3fb504f3, v244
	global_store_dword v167, v93, s[28:29] offset:192
	s_waitcnt vmcnt(41)
	v_sub_f32_e32 v245, v245, v144
	v_mul_f32_e32 v245, v245, v145
	v_fma_f32 v245, v18, v245, v34
	v_mul_f32_e32 v94, v94, v176
	v_fmac_f32_e32 v94, 0x3fb504f3, v245
	global_store_dword v168, v94, s[28:29] offset:-3904
	s_waitcnt vmcnt(40)
	v_sub_f32_e32 v112, v112, v146
	v_mul_f32_e32 v112, v112, v147
	v_fma_f32 v112, v18, v112, v34
	v_mul_f32_e32 v95, v95, v176
	v_fmac_f32_e32 v95, 0x3fb504f3, v112
	global_store_dword v168, v95, s[28:29] offset:192
	s_waitcnt vmcnt(39)
	v_sub_f32_e32 v115, v115, v148
	v_mul_f32_e32 v115, v115, v149
	v_fma_f32 v115, v18, v115, v34
	v_mul_f32_e32 v108, v108, v176
	v_fmac_f32_e32 v108, 0x3fb504f3, v115
	global_store_dword v169, v108, s[28:29] offset:-3904
	s_waitcnt vmcnt(38)
	v_sub_f32_e32 v208, v208, v150
	v_mul_f32_e32 v208, v208, v151
	v_fma_f32 v208, v18, v208, v34
	v_mul_f32_e32 v109, v109, v176
	v_fmac_f32_e32 v109, 0x3fb504f3, v208
	global_store_dword v169, v109, s[28:29] offset:192
	s_waitcnt vmcnt(37)
	v_sub_f32_e32 v223, v223, v152
	v_mul_f32_e32 v223, v223, v153
	v_fma_f32 v223, v18, v223, v34
	v_mul_f32_e32 v110, v110, v176
	v_fmac_f32_e32 v110, 0x3fb504f3, v223
	global_store_dword v170, v110, s[28:29] offset:-3904
	s_waitcnt vmcnt(36)
	v_sub_f32_e32 v233, v233, v154
	v_mul_f32_e32 v233, v233, v155
	v_fma_f32 v233, v18, v233, v34
	v_mul_f32_e32 v111, v111, v176
	v_fmac_f32_e32 v111, 0x3fb504f3, v233
	global_store_dword v170, v111, s[28:29] offset:192
	s_waitcnt vmcnt(35)
	v_sub_f32_e32 v248, v248, v156
	v_mul_f32_e32 v248, v248, v157
	v_fma_f32 v248, v18, v248, v34
	v_mul_f32_e32 v128, v128, v176
	v_fmac_f32_e32 v128, 0x3fb504f3, v248
	global_store_dword v171, v128, s[28:29] offset:-3904
	s_waitcnt vmcnt(34)
	v_sub_f32_e32 v0, v0, v158
	v_mul_f32_e32 v0, v0, v159
	v_fma_f32 v0, v18, v0, v34
	v_mul_f32_e32 v129, v129, v176
	v_fmac_f32_e32 v129, 0x3fb504f3, v0
	global_store_dword v171, v129, s[28:29] offset:192
	s_waitcnt vmcnt(33)
	v_sub_f32_e32 v1, v1, v160
	v_mul_f32_e32 v1, v1, v161
	v_fma_f32 v1, v18, v1, v34
	v_mul_f32_e32 v130, v130, v176
	v_fmac_f32_e32 v130, 0x3fb504f3, v1
	global_store_dword v172, v130, s[28:29] offset:-3904
	s_waitcnt vmcnt(32)
	v_sub_f32_e32 v2, v2, v162
	v_mul_f32_e32 v2, v2, v163
	v_fma_f32 v2, v18, v2, v34
	v_mul_f32_e32 v131, v131, v176
	v_fmac_f32_e32 v131, 0x3fb504f3, v2
	global_store_dword v172, v131, s[28:29] offset:192
	s_add_i32 s11, s11, s59
	s_cmpk_gt_i32 s11, 0x3ff
	s_cbranch_scc0 .LBB0_649
	v_mov_b32_e32 v113, 0
	v_mov_b32_e32 v114, 0x3f317218
